# scan loader: scan_issue moved ahead of scan_finish (previously loaded registers copied to shadow VGPRs at the top of the iteration; finish has no vmcnt waits)
# speedup vs baseline: 1.0035x; 1.0035x over previous
; #define KP(f) ((decltype(Params::f))karg_ptr<(int)offsetof(Params, f)>())
; __device__ void phase_scan(int l, unsigned char* lds) {
;     int tid_ = threadIdx.x; asm volatile("" : "+v"(tid_));
;     const int tid = tid_, wid = tid >> 6, lane = tid & 63, G = gridDim.x;
;     const bool loader = wid >= 4;
;     if (!loader) __builtin_amdgcn_s_setprio(3);
;     ScanPtrs Q;
;     Q.z = KP(z); Q.sw = KP(xb) + (size_t)T_ALL * 512; Q.sa = KP(sc_a); Q.st_shift = KP(state_shift) + (size_t)l * NSB * DSH; Q.mu = KP(mu_shift) + (size_t)l * DSH;
;     Q.k_k = KP(k_k) + (size_t)l * 512; Q.k_a = KP(k_a) + (size_t)l * 512; Q.r_k = KP(r_k) + (size_t)l * 512; Q.decay0 = KP(decay0) + (size_t)l * 512; Q.a0 = KP(a0) + (size_t)l * 512; Q.rk = KP(rk);
;     bf16_t* ybuf = KP(xb);
;     const float* st_wkv = KP(state_wkv); float* out = KP(out);
;     int J = (G % 8 == 0) ? (int)(blockIdx.x % 8) * (G / 8) + (int)(blockIdx.x / 8) : (int)blockIdx.x, ci = 0, it = 0;
;     int Ji = J, cis = 0;
;     int Jg = J, cg_ = 0;
;     LStage L, L2;
;     f32x2 s01 = (f32x2){0.f, 0.f}, s23 = s01;
;     f32x4 s_pref = (f32x4){0.f, 0.f, 0.f, 0.f};
;     if (!loader && J >= 256 && J < NJOBS) { const Job j0 = job_decode(J, 0); s_pref = *(const f32x4*)(st_wkv + (((((size_t)l * NSB + j0.seq) * 8 + j0.h) * 64 + j0.rs * 16 + (wid * 4 + (lane >> 4))) * 64 + (lane & 15) * 4)); }
.LBB0_401:
	s_or_b64 exec, exec, s[8:9]
	s_mov_b32 s6, s46
	s_mov_b32 s7, s2
	v_mov_b32_e32 v53, v166
	s_waitcnt lgkmcnt(0)
	s_barrier
	s_nop 0
	v_ashrrev_i32_e32 v52, 6, v53
	s_mov_b32 s98, -1
	s_mov_b32 s99, 0
	v_cmp_lt_i32_e64 s[10:11], 3, v52
	v_cmp_gt_i32_e64 s[12:13], 4, v52
	s_and_saveexec_b64 s[8:9], s[12:13]
	s_setprio 3
	s_or_b64 exec, exec, s[8:9]
	s_load_dwordx2 s[24:25], s[0:1], 0x130
	s_waitcnt lgkmcnt(0)
	s_load_dwordx2 s[14:15], s[0:1], 0x120
	s_waitcnt lgkmcnt(0)
	s_load_dwordx2 s[26:27], s[0:1], 0x140
	s_waitcnt lgkmcnt(0)
	s_load_dwordx2 s[28:29], s[0:1], 16
	s_waitcnt lgkmcnt(0)
	s_load_dwordx2 s[30:31], s[0:1], 56
	s_waitcnt lgkmcnt(0)
	s_load_dwordx2 s[34:35], s[0:1], 0x68
	s_waitcnt lgkmcnt(0)
	s_load_dwordx2 s[36:37], s[0:1], 0x70
	s_waitcnt lgkmcnt(0)
	s_load_dwordx2 s[38:39], s[0:1], 0x78
	s_waitcnt lgkmcnt(0)
	s_load_dwordx2 s[40:41], s[0:1], 64
	s_waitcnt lgkmcnt(0)
	s_load_dwordx2 s[56:57], s[0:1], 0x50
	s_waitcnt lgkmcnt(0)
	s_load_dwordx2 s[58:59], s[0:1], 0x150
	s_waitcnt lgkmcnt(0)
	s_load_dwordx2 s[60:61], s[0:1], 0x120
	s_waitcnt lgkmcnt(0)
	s_load_dwordx2 s[22:23], s[0:1], 32
	s_waitcnt lgkmcnt(0)
	s_load_dwordx2 s[62:63], s[0:1], 0xd8
	s_waitcnt lgkmcnt(0)
	v_cndmask_b32_e64 v0, 0, 1, s[54:55]
	v_cmp_ne_u32_e64 s[6:7], 1, v0
	s_andn2_b64 vcc, exec, s[54:55]
	s_mov_b32 s51, s2
	v_writelane_b32 v230, s6, 6
	s_nop 1
	v_writelane_b32 v230, s7, 7
	s_cbranch_vccnz .LBB0_405
	s_and_b32 s6, s2, 7
	s_ashr_i32 s7, s46, 3
	s_mul_i32 s6, s7, s6
	s_lshr_b32 s7, s2, 3
	s_add_i32 s51, s6, s7

; #define SC_ADV(J_, c_) do { if ((J_) < NJOBS) { if (++(c_) >= ((J_) < 256 ? SEQ / SC_CH : 1)) { (J_) += G; (c_) = 0; } } } while (0)
; __device__ void phase_scan(int l, unsigned char* lds) {
;     ...
;     while (J < NJOBS) {
;         int Jn = J, cn = ci; SC_ADV(Jn, cn);
;         const unsigned char* buf = lds + (it % 3) * SC_BUFB;
;         if (loader) {
;             if (Jg < NJOBS) { scan_finish(Q, Jg, cg_, lds + ((it + 2) % 3) * SC_BUFB, tid - 256, L, 0); scan_finish(Q, Jg, cg_, lds + ((it + 2) % 3) * SC_BUFB, tid - 256, L2, 16); }
;             SC_ADV(Jg, cg_);
;             if (Ji < NJOBS) { scan_issue(Q, Ji, cis, tid - 256, L, 0); scan_issue(Q, Ji, cis, tid - 256, L2, 16); }
.LBB0_475:
	s_add_i32 s8, s64, 1
	s_cmpk_gt_i32 s51, 0xff
	s_cselect_b64 s[68:69], -1, 0
	s_cmpk_lt_i32 s51, 0x100
	s_cselect_b64 s[66:67], -1, 0
	s_and_b64 s[6:7], s[66:67], exec
	s_cselect_b32 s6, 64, 1
	s_cmp_lt_i32 s8, s6
	s_cselect_b32 s84, s8, 0
	s_cselect_b32 s85, 0, s46
	s_and_saveexec_b64 s[6:7], s[10:11]
	s_xor_b64 s[70:71], exec, s[6:7]
	s_cbranch_execz .LBB0_522
	s_cmp_lg_u32 s99, 0
	s_cbranch_scc1 .Lld_w1_0
	s_waitcnt vmcnt(0)
	s_branch .Lld_wd_0
.Lld_w1_0:
	s_cmp_lg_u32 s99, 1
	s_cbranch_scc1 .Lld_w2_0
	s_waitcnt vmcnt(1)
	s_branch .Lld_wd_0
.Lld_w2_0:
	s_waitcnt vmcnt(2)
.Lld_wd_0:
	s_mov_b32 s99, 0
	v_mov_b64_e32 v[218:219], v[6:7]
	v_mov_b64_e32 v[220:221], v[8:9]
	v_mov_b64_e32 v[222:223], v[10:11]
	v_mov_b64_e32 v[224:225], v[12:13]
	v_mov_b64_e32 v[226:227], v[14:15]
	v_mov_b64_e32 v[228:229], v[16:17]
	v_mov_b64_e32 v[170:171], v[54:55]
	v_mov_b64_e32 v[172:173], v[56:57]
	v_mov_b64_e32 v[174:175], v[58:59]
	v_mov_b64_e32 v[176:177], v[60:61]
	v_mov_b64_e32 v[178:179], v[62:63]
	v_mov_b64_e32 v[180:181], v[64:65]
	v_mov_b64_e32 v[182:183], v[66:67]
	v_mov_b64_e32 v[184:185], v[68:69]
	v_mov_b64_e32 v[232:233], v[70:71]
	v_mov_b64_e32 v[234:235], v[72:73]
	v_mov_b64_e32 v[236:237], v[74:75]
	v_mov_b64_e32 v[238:239], v[76:77]
	v_mov_b64_e32 v[240:241], v[78:79]
	v_mov_b64_e32 v[242:243], v[80:81]
	v_mov_b64_e32 v[244:245], v[82:83]
	v_mov_b64_e32 v[246:247], v[84:85]
	v_cmp_gt_i32_e32 vcc, s77, v1
	s_and_saveexec_b64 s[20:21], vcc
	s_cbranch_execz .LBB0_521
	v_cmp_lt_i32_e32 vcc, s53, v1
	v_cmp_gt_i32_e64 s[16:17], s76, v1
	s_and_saveexec_b64 s[6:7], s[16:17]
	s_xor_b64 s[18:19], exec, s[6:7]
	s_cbranch_execz .LBB0_512
	v_ashrrev_i32_e32 v21, 5, v1
	v_lshlrev_b32_e32 v18, 5, v0
	v_lshl_add_u32 v18, v21, 11, v18
	s_or_saveexec_b64 s[18:19], s[18:19]
	v_mov_b32_e32 v20, 32
	s_xor_b64 exec, exec, s[18:19]
	s_cbranch_execnz .LBB0_513

; __device__ __forceinline__ f32x4 cv_bf4(const u32x2 w) { return (f32x4){bflo(w.x), bfhi(w.x), bflo(w.y), bfhi(w.y)}; }
; __device__ __forceinline__ void scan_finish(const ScanPtrs& Q, int J, int ci, unsigned char* buf, int ltid, const LStage& L, int toff) {
;     const Job jb = job_decode(J, ci);
;     const int tt = (ltid >> 4) + toff, c = (ltid & 15) * 4;
;     if (tt < jb.nsteps) {
;         const int tok = jb.tok0 + tt; const int tseq = jb.is_s ? tt : ci * SC_CH + tt;
;         const int gc = jb.h * 64 + c;
;         f32x4 r = cv_bf4(L.r), k0 = cv_bf4(L.k), v = cv_bf4(L.v), rp, kp, vp;
;         if (tseq > 0) { rp = cv_bf4(L.rp); kp = cv_bf4(L.kp); vp = cv_bf4(L.vp); }
;         else if (jb.is_s) { rp = L.fr; kp = L.fk; vp = L.fv; }
;         else { rp = (f32x4){0.f, 0.f, 0.f, 0.f}; kp = rp; vp = rp; }
.LBB0_521:
	s_or_b64 exec, exec, s[20:21]
	v_cmp_gt_i32_e32 vcc, s77, v94
	s_and_saveexec_b64 s[72:73], vcc
	s_cbranch_execz .LBB0_501
	v_cmp_lt_i32_e64 s[16:17], s53, v94
	v_cmp_gt_i32_e32 vcc, s76, v94
	s_and_saveexec_b64 s[6:7], vcc
	s_xor_b64 s[18:19], exec, s[6:7]
	v_lshlrev_b32_e32 v18, 6, v94
	v_and_b32_e32 v18, 0xfffff800, v18
	v_lshl_add_u32 v122, v95, 5, v18
	s_or_saveexec_b64 s[18:19], s[18:19]
	v_mov_b32_e32 v18, 32
	s_xor_b64 exec, exec, s[18:19]
	v_add_u32_e32 v18, 0xffffff00, v94
	v_lshrrev_b32_e32 v18, 2, v18
	v_and_b32_e32 v18, 0x3ffffff8, v18
	v_add_u32_e32 v122, 0x4000, v18
	v_mov_b32_e32 v18, 8
	s_or_b64 exec, exec, s[18:19]
	s_add_i32 s6, s83, 2
	s_mul_hi_u32 s7, s6, 0xaaaaaaab
	s_lshr_b32 s7, s7, 1
	s_mul_i32 s7, s7, 3
	s_sub_i32 s6, s6, s7
	s_mul_i32 s6, s6, 0xa800
	s_add_i32 s6, s6, 0
	v_and_b32_e32 v121, 3, v94
	v_bfe_u32 v91, v94, 2, 3
	v_cmp_lt_u32_e32 vcc, v96, v18
	v_lshlrev_b32_e32 v120, 5, v95
	s_and_saveexec_b64 s[74:75], vcc
	s_cbranch_execz .LBB0_492
	v_cndmask_b32_e64 v18, v120, 0, s[16:17]
	v_cmp_le_i32_e32 vcc, v18, v98
	s_and_saveexec_b64 s[8:9], vcc
	s_xor_b64 s[18:19], exec, s[8:9]
	s_cbranch_execz .LBB0_486
	v_mov_b32_e32 v20, v19
	v_mov_b32_e32 v21, v19
	v_mov_b32_e32 v18, v19
	v_mov_b64_e32 v[48:49], v[20:21]
	v_mov_b64_e32 v[52:53], v[20:21]
	v_mov_b64_e32 v[28:29], v[20:21]
	v_mov_b64_e32 v[46:47], v[18:19]
	v_mov_b64_e32 v[50:51], v[18:19]
	v_mov_b64_e32 v[26:27], v[18:19]
	s_and_saveexec_b64 s[20:21], s[16:17]
	s_cbranch_execz .LBB0_485
	v_mov_b64_e32 v[48:49], v[220:221]
	v_mov_b64_e32 v[52:53], v[224:225]
	v_mov_b64_e32 v[28:29], v[228:229]
	v_mov_b64_e32 v[46:47], v[218:219]
	v_mov_b64_e32 v[50:51], v[222:223]
	v_mov_b64_e32 v[26:27], v[226:227]

; __device__ __forceinline__ f32x4 cv_bf4(const u32x2 w) { return (f32x4){bflo(w.x), bfhi(w.x), bflo(w.y), bfhi(w.y)}; }
; __device__ __forceinline__ void scan_finish(const ScanPtrs& Q, int J, int ci, unsigned char* buf, int ltid, const LStage& L, int toff) {
;     ...
;         f32x4 r = cv_bf4(L.r), k0 = cv_bf4(L.k), v = cv_bf4(L.v), rp, kp, vp;
;         if (tseq > 0) { rp = cv_bf4(L.rp); kp = cv_bf4(L.kp); vp = cv_bf4(L.vp); }
;         else if (jb.is_s) { rp = L.fr; kp = L.fk; vp = L.fv; }
;         else { rp = (f32x4){0.f, 0.f, 0.f, 0.f}; kp = rp; vp = rp; }
;         const float* mu = Q.mu + gc;
;         r = r + (rp - r) * *(const f32x4*)mu; k0 = k0 + (kp - k0) * *(const f32x4*)(mu + 512); v = v + (vp - v) * *(const f32x4*)(mu + 1024);
;         const f32x4 kk = k0 * *(const f32x4*)(Q.k_k + gc);
;         const float ss = allsum16((kk[0] * kk[0] + kk[1] * kk[1]) + (kk[2] * kk[2] + kk[3] * kk[3]));
;         const float inv = 1.0f / fmaxf(sqrtf(ss), 1e-12f);
;         const f32x4 kkn = kk * inv;
;         const f32x4 dw = cv_bf4(L.sw) + *(const f32x4*)(Q.decay0 + gc);
;         const f32x4 da = cv_bf4(L.sa) + *(const f32x4*)(Q.a0 + gc);
.LBB0_486:
	s_andn2_saveexec_b64 s[18:19], s[18:19]
	s_cbranch_execz .LBB0_488
	v_lshlrev_b32_e32 v46, 16, v180
	v_and_b32_e32 v47, 0xffff0000, v180
	v_lshlrev_b32_e32 v48, 16, v181
	v_and_b32_e32 v49, 0xffff0000, v181
	v_lshlrev_b32_e32 v50, 16, v236
	v_and_b32_e32 v51, 0xffff0000, v236
	v_lshlrev_b32_e32 v52, 16, v237
	v_and_b32_e32 v53, 0xffff0000, v237
	v_lshlrev_b32_e32 v26, 16, v238
	v_and_b32_e32 v27, 0xffff0000, v238
	v_lshlrev_b32_e32 v28, 16, v239
	v_and_b32_e32 v29, 0xffff0000, v239
.LBB0_488:
	s_or_b64 exec, exec, s[18:19]
	v_lshl_or_b32 v18, v91, 8, v100
	v_readfirstlane_b32 s100, v91
	s_nop 3
	s_cmp_eq_u32 s100, s98
	s_cbranch_scc1 .Lprm_ok_0
	s_mov_b32 s98, s100
	s_lshl_b32 s100, s100, 8
	v_or_b32_e32 v251, s100, v100
	global_load_dwordx4 v[186:189], v251, s[30:31] offset:2048
	global_load_dwordx4 v[190:193], v251, s[40:41]
	global_load_dwordx4 v[194:197], v251, s[56:57]
	global_load_dwordx4 v[198:201], v251, s[34:35]
	global_load_dwordx4 v[202:205], v251, s[30:31]
	global_load_dwordx4 v[206:209], v251, s[36:37]
	global_load_dwordx4 v[210:213], v251, s[38:39]
	v_add_u32_e32 v250, 0x1000, v251
	global_load_dwordx4 v[214:217], v250, s[30:31]
	s_waitcnt vmcnt(0)
.Lprm_ok_0:
	v_lshlrev_b32_e32 v132, 16, v232
	v_and_b32_e32 v133, 0xffff0000, v232
	v_lshlrev_b32_e32 v134, 16, v233
	v_and_b32_e32 v135, 0xffff0000, v233
	v_sub_f32_e32 v137, v51, v133
	v_sub_f32_e32 v136, v50, v132
	v_sub_f32_e32 v139, v53, v135
	v_sub_f32_e32 v138, v52, v134
	v_lshlrev_b32_e32 v123, 16, v244
	v_and_b32_e32 v140, 0xffff0000, v244
	v_lshlrev_b32_e32 v141, 16, v245
	v_lshlrev_b32_e32 v143, 16, v246
	v_and_b32_e32 v142, 0xffff0000, v245
	v_and_b32_e32 v146, 0xffff0000, v246
	v_lshlrev_b32_e32 v147, 16, v247
	v_and_b32_e32 v148, 0xffff0000, v247
	v_lshlrev_b32_e32 v20, 16, v178
	v_and_b32_e32 v21, 0xffff0000, v178
	v_lshlrev_b32_e32 v92, 16, v179
	v_and_b32_e32 v93, 0xffff0000, v179
	v_sub_f32_e32 v47, v47, v21
	v_sub_f32_e32 v46, v46, v20
	v_sub_f32_e32 v49, v49, v93
	v_sub_f32_e32 v48, v48, v92
	v_pk_fma_f32 v[44:45], v[138:139], v[188:189], v[134:135]
	v_pk_fma_f32 v[42:43], v[136:137], v[186:187], v[132:133]
	v_add_f32_e32 v38, v190, v123
	v_add_f32_e32 v39, v191, v140
	v_pk_mul_f32 v[126:127], v[44:45], v[200:201]
	v_pk_mul_f32 v[124:125], v[42:43], v[198:199]
	v_mul_f32_e32 v123, 0xbfb8aa3b, v38
	v_mul_f32_e32 v134, 0xbfb8aa3b, v39
	v_pk_mul_f32 v[38:39], v[126:127], v[126:127]
	v_pk_mul_f32 v[132:133], v[124:125], v[124:125]
	v_exp_f32_e32 v123, v123
	v_exp_f32_e32 v136, v134
	v_pk_mov_b32 v[134:135], v[132:133], v[38:39] op_sel:[1,0]
	v_mov_b32_e32 v133, v39
	v_pk_add_f32 v[38:39], v[134:135], v[132:133]
	v_add_f32_e32 v40, v192, v141
	v_add_f32_e32 v38, v38, v39
	v_add_f32_e32 v39, 1.0, v123
	v_add_f32_e32 v123, 1.0, v136
	v_add_f32_dpp v38, v38, v38 quad_perm:[1,0,3,2] row_mask:0xf bank_mask:0xf bound_ctrl:1
	v_div_scale_f32 v132, s[8:9], v39, v39, 1.0
	s_nop 0
	v_add_f32_dpp v38, v38, v38 quad_perm:[2,3,0,1] row_mask:0xf bank_mask:0xf bound_ctrl:1
	v_div_scale_f32 v134, s[8:9], v123, v123, 1.0
	s_nop 0
	v_add_f32_dpp v38, v38, v38 row_half_mirror row_mask:0xf bank_mask:0xf bound_ctrl:1
	v_rcp_f32_e32 v136, v132
	v_rcp_f32_e32 v137, v134
	v_add_f32_dpp v38, v38, v38 row_mirror row_mask:0xf bank_mask:0xf bound_ctrl:1
	v_mul_f32_e32 v138, 0x4f800000, v38
	v_cmp_gt_f32_e32 vcc, s78, v38
	v_fma_f32 v139, -v132, v136, 1.0
	v_div_scale_f32 v133, s[18:19], 1.0, v39, 1.0
	v_cndmask_b32_e32 v38, v38, v138, vcc
	v_sqrt_f32_e32 v138, v38
	v_fma_f32 v140, -v134, v137, 1.0
	v_fmac_f32_e32 v136, v139, v136
	v_div_scale_f32 v135, s[20:21], 1.0, v123, 1.0
	v_fmac_f32_e32 v137, v140, v137
	v_mul_f32_e32 v139, v133, v136
	v_mul_f32_e32 v140, v135, v137
	v_fma_f32 v141, -v132, v139, v133
	v_add_u32_e32 v149, -1, v138
	v_add_f32_e32 v34, v194, v143
	v_fma_f32 v143, -v134, v140, v135
	v_add_u32_e32 v150, 1, v138
	v_fmac_f32_e32 v139, v141, v136
	v_fma_f32 v141, -v149, v138, v38
	v_fmac_f32_e32 v140, v143, v137
	v_fma_f32 v143, -v150, v138, v38
	v_cmp_ge_f32_e64 s[22:23], 0, v141
	v_fma_f32 v133, -v132, v139, v133
	v_fma_f32 v134, -v134, v140, v135
	v_cndmask_b32_e64 v132, v138, v149, s[22:23]
	v_cmp_lt_f32_e64 s[22:23], 0, v143
	v_mul_f32_e32 v40, 0xbfb8aa3b, v40
	v_exp_f32_e32 v40, v40
	v_cndmask_b32_e64 v132, v132, v150, s[22:23]
	v_mul_f32_e32 v138, 0x37800000, v132
	v_cndmask_b32_e32 v132, v132, v138, vcc
	v_cmp_class_f32_e32 vcc, v38, v118
	v_add_f32_e32 v40, 1.0, v40
	v_add_f32_e32 v41, v193, v142
	v_cndmask_b32_e32 v38, v132, v38, vcc
	v_max_f32_e32 v38, 0x2b8cbccc, v38
	v_div_scale_f32 v132, s[8:9], v38, v38, -1.0
	v_rcp_f32_e32 v138, v132
	v_div_scale_f32 v135, vcc, -1.0, v38, -1.0
	v_mul_f32_e32 v41, 0xbfb8aa3b, v41
	v_fma_f32 v141, -v132, v138, 1.0
	v_fmac_f32_e32 v138, v141, v138
	v_mul_f32_e32 v141, v135, v138
	v_fma_f32 v143, -v132, v141, v135
	v_fmac_f32_e32 v141, v143, v138
	v_fma_f32 v132, -v132, v141, v135
	v_div_fmas_f32 v132, v132, v138, v141
	s_mov_b64 vcc, s[18:19]
	v_div_fixup_f32 v132, v132, v38, -1.0
	v_div_fmas_f32 v38, v133, v136, v139
	s_mov_b64 vcc, s[20:21]
	v_div_fixup_f32 v38, v38, v39, 1.0
	v_div_fmas_f32 v39, v134, v137, v140
	v_div_fixup_f32 v39, v39, v123, 1.0
	v_div_scale_f32 v123, s[8:9], v40, v40, 1.0
	v_rcp_f32_e32 v133, v123
	v_exp_f32_e32 v41, v41
	v_add_f32_e32 v35, v195, v146
	v_mul_f32_e32 v34, 0xbfb8aa3b, v34
	v_fma_f32 v134, -v123, v133, 1.0
	v_fmac_f32_e32 v133, v134, v133
	v_div_scale_f32 v134, vcc, 1.0, v40, 1.0
	v_mul_f32_e32 v135, v134, v133
	v_fma_f32 v136, -v123, v135, v134
	v_fmac_f32_e32 v135, v136, v133
	v_fma_f32 v123, -v123, v135, v134
	v_div_fmas_f32 v123, v123, v133, v135
	v_add_f32_e32 v41, 1.0, v41
; __device__ __forceinline__ float sigmoidf_(float x) { return 1.0f / (1.0f + __expf(-x)); }
; __device__ __forceinline__ f32x4 cv_bf4(const u32x2 w) { return (f32x4){bflo(w.x), bfhi(w.x), bflo(w.y), bfhi(w.y)}; }
; __device__ __forceinline__ void scan_finish(const ScanPtrs& Q, int J, int ci, unsigned char* buf, int ltid, const LStage& L, int toff) {
;     ...
;         const f32x4 dw = cv_bf4(L.sw) + *(const f32x4*)(Q.decay0 + gc);
;         const f32x4 da = cv_bf4(L.sa) + *(const f32x4*)(Q.a0 + gc);
;         f32x4 dec, ain;
; #pragma unroll
;         for (int j = 0; j < 4; ++j) { dec[j] = __expf(-0.60653066f * sigmoidf_(dw[j])); ain[j] = sigmoidf_(da[j]); }
;         const f32x4 ka = *(const f32x4*)(Q.k_a + gc);
;         const f32x4 kf = k0 * (1.0f + (ain - 1.0f) * ka);
;         const f32x4 rkw = *(const f32x4*)(Q.r_k + gc);
;         const f32x4 pr = r * kf * rkw;
;         const float rk = allsum16((pr[0] + pr[1]) + (pr[2] + pr[3]));
;         unsigned char* tb = buf + tt * SC_TOKB + c * 4;
;         *(f32x4*)(tb) = -kkn; *(f32x4*)(tb + 256) = dec; *(f32x4*)(tb + 512) = kkn * ain; *(f32x4*)(tb + 768) = kf; *(f32x4*)(tb + 1024) = r;
;         if ((c >> 4) == jb.rs) *(f32x4*)(buf + tt * SC_TOKB + 1280 + (c & 15) * 4) = v;
;         if (jb.rs == 0 && c == 0) Q.rk[(size_t)tok * 8 + jb.h] = rk;
	v_div_fixup_f32 v40, v123, v40, 1.0
	v_div_scale_f32 v123, s[8:9], v41, v41, 1.0
	v_rcp_f32_e32 v133, v123
	v_mul_f32_e32 v35, 0xbfb8aa3b, v35
	v_exp_f32_e32 v34, v34
	v_exp_f32_e32 v35, v35
	v_fma_f32 v134, -v123, v133, 1.0
	v_fmac_f32_e32 v133, v134, v133
	v_div_scale_f32 v134, vcc, 1.0, v41, 1.0
	v_mul_f32_e32 v135, v134, v133
	v_fma_f32 v136, -v123, v135, v134
	v_fmac_f32_e32 v135, v136, v133
	v_fma_f32 v123, -v123, v135, v134
	v_div_fmas_f32 v123, v123, v133, v135
	v_pk_add_f32 v[34:35], v[34:35], 1.0 op_sel_hi:[1,0]
	v_div_fixup_f32 v41, v123, v41, 1.0
	v_div_scale_f32 v123, s[8:9], v35, v35, 1.0
	v_rcp_f32_e32 v133, v123
	v_add_f32_e32 v36, v196, v147
	v_add_f32_e32 v37, v197, v148
	v_mul_f32_e32 v36, 0xbfb8aa3b, v36
	v_fma_f32 v134, -v123, v133, 1.0
	v_fmac_f32_e32 v133, v134, v133
	v_div_scale_f32 v134, vcc, 1.0, v35, 1.0
	v_mul_f32_e32 v135, v134, v133
	v_fma_f32 v136, -v123, v135, v134
	v_fmac_f32_e32 v135, v136, v133
	v_fma_f32 v123, -v123, v135, v134
	v_div_scale_f32 v134, s[8:9], v34, v34, 1.0
	v_rcp_f32_e32 v136, v134
	v_mul_f32_e32 v37, 0xbfb8aa3b, v37
	v_exp_f32_e32 v36, v36
	v_exp_f32_e32 v37, v37
	v_div_fmas_f32 v123, v123, v133, v135
	v_div_fixup_f32 v135, v123, v35, 1.0
	v_fma_f32 v35, -v134, v136, 1.0
	v_fmac_f32_e32 v136, v35, v136
	v_div_scale_f32 v35, vcc, 1.0, v34, 1.0
	v_mul_f32_e32 v123, v35, v136
	v_pk_add_f32 v[36:37], v[36:37], 1.0 op_sel_hi:[1,0]
	v_fma_f32 v133, -v134, v123, v35
	v_fmac_f32_e32 v123, v133, v136
	v_div_scale_f32 v133, s[8:9], v37, v37, 1.0
	v_rcp_f32_e32 v137, v133
	v_fma_f32 v35, -v134, v123, v35
	v_div_fmas_f32 v35, v35, v136, v123
	v_div_fixup_f32 v134, v35, v34, 1.0
	v_fma_f32 v34, -v133, v137, 1.0
	v_fmac_f32_e32 v137, v34, v137
	v_div_scale_f32 v34, vcc, 1.0, v37, 1.0
	v_mul_f32_e32 v35, v34, v137
	v_fma_f32 v123, -v133, v35, v34
	v_fmac_f32_e32 v35, v123, v137
	v_div_scale_f32 v123, s[8:9], v36, v36, 1.0
	v_fma_f32 v34, -v133, v35, v34
	v_rcp_f32_e32 v133, v123
	v_div_fmas_f32 v34, v34, v137, v35
	v_div_fixup_f32 v37, v34, v37, 1.0
	v_mul_f32_e32 v38, 0xbf1b4598, v38
	v_fma_f32 v34, -v123, v133, 1.0
	v_fmac_f32_e32 v133, v34, v133
	v_div_scale_f32 v34, vcc, 1.0, v36, 1.0
	v_mul_f32_e32 v35, v34, v133
	v_fma_f32 v136, -v123, v35, v34
	v_fmac_f32_e32 v35, v136, v133
	v_fma_f32 v34, -v123, v35, v34
	v_div_fmas_f32 v34, v34, v133, v35
	v_div_fixup_f32 v36, v34, v36, 1.0
	v_pk_fma_f32 v[34:35], v[48:49], v[204:205], v[92:93]
	v_pk_fma_f32 v[32:33], v[46:47], v[202:203], v[20:21]
	v_pk_add_f32 v[20:21], v[36:37], -1.0 op_sel_hi:[1,0]
	v_pk_add_f32 v[30:31], v[134:135], -1.0 op_sel_hi:[1,0]
	v_pk_fma_f32 v[20:21], v[208:209], v[20:21], 1.0 op_sel_hi:[1,1,0]
	v_pk_fma_f32 v[30:31], v[206:207], v[30:31], 1.0 op_sel_hi:[1,1,0]
	v_pk_mul_f32 v[44:45], v[44:45], v[20:21]
	v_pk_mul_f32 v[42:43], v[42:43], v[30:31]
	v_pk_mul_f32 v[30:31], v[34:35], v[44:45]
	v_pk_mul_f32 v[20:21], v[32:33], v[42:43]
	v_pk_mul_f32 v[30:31], v[212:213], v[30:31]
	v_pk_mul_f32 v[20:21], v[210:211], v[20:21]
	v_mul_f32_e32 v39, 0xbf1b4598, v39
	v_mul_f32_e32 v40, 0xbf1b4598, v40
	v_mul_f32_e32 v41, 0xbf1b4598, v41
	v_add_f32_e32 v20, v20, v21
	v_add_f32_e32 v21, v30, v31
	v_mul_f32_e32 v38, 0x3fb8aa3b, v38
	v_mul_f32_e32 v39, 0x3fb8aa3b, v39
	v_mul_f32_e32 v40, 0x3fb8aa3b, v40
	v_mul_f32_e32 v41, 0x3fb8aa3b, v41
	v_add_f32_e32 v20, v20, v21
	v_exp_f32_e32 v38, v38
	v_exp_f32_e32 v39, v39
	v_exp_f32_e32 v40, v40
	v_exp_f32_e32 v41, v41
	v_add_f32_dpp v20, v20, v20 quad_perm:[1,0,3,2] row_mask:0xf bank_mask:0xf bound_ctrl:1
	v_add_u32_e32 v30, s6, v99
	v_mov_b32_e32 v21, 0
	v_add_f32_dpp v20, v20, v20 quad_perm:[2,3,0,1] row_mask:0xf bank_mask:0xf bound_ctrl:1
	v_add_u32_e32 v31, v30, v100
	v_pk_mul_f32 v[48:49], v[126:127], v[132:133] op_sel_hi:[1,0]
	v_add_f32_dpp v20, v20, v20 row_half_mirror row_mask:0xf bank_mask:0xf bound_ctrl:1
	v_pk_mul_f32 v[46:47], v[124:125], v[132:133] op_sel_hi:[1,0]
	ds_write_b128 v31, v[46:49]
	ds_write_b128 v31, v[38:41] offset:256
	v_mov_b32_dpp v21, v20 row_mirror row_mask:0xf bank_mask:0xf
	v_pk_mul_f32 v[38:39], v[48:49], v[36:37] neg_lo:[1,0] neg_hi:[1,0]
	v_pk_mul_f32 v[36:37], v[46:47], v[134:135] neg_lo:[1,0] neg_hi:[1,0]
	v_cmp_eq_u32_e32 vcc, v101, v121
	ds_write_b128 v31, v[36:39] offset:512
	ds_write_b128 v31, v[42:45] offset:768
	ds_write_b128 v31, v[32:35] offset:1024
	s_and_saveexec_b64 s[18:19], vcc
	s_cbranch_execz .LBB0_490
	v_lshl_add_u64 v[32:33], s[30:31], 0, v[18:19]
	v_add_co_u32_e32 v32, vcc, 0x1000, v32
	v_lshlrev_b32_e32 v36, 16, v234
	s_nop 0
	v_addc_co_u32_e32 v33, vcc, 0, v33, vcc
	v_and_b32_e32 v37, 0xffff0000, v234
	v_lshlrev_b32_e32 v38, 16, v235
	v_and_b32_e32 v39, 0xffff0000, v235
	v_sub_f32_e32 v29, v29, v39
	v_sub_f32_e32 v28, v28, v38
	v_sub_f32_e32 v27, v27, v37
	v_sub_f32_e32 v26, v26, v36
	v_add_u32_e32 v18, v30, v102
	v_pk_fma_f32 v[26:27], v[26:27], v[214:215], v[36:37]
	v_pk_fma_f32 v[28:29], v[28:29], v[216:217], v[38:39]
	ds_write_b128 v18, v[26:29] offset:1280
.LBB0_490:
	s_or_b64 exec, exec, s[18:19]
	v_or_b32_e32 v18, v121, v97
	v_cmp_eq_u32_e32 vcc, 0, v18
	s_and_b64 exec, exec, vcc
	s_cbranch_execz .LBB0_492
	v_add_f32_e32 v26, v20, v21
	v_add_u32_e32 v20, v122, v96
	v_ashrrev_i32_e32 v21, 31, v20
	v_lshlrev_b64 v[20:21], 5, v[20:21]
	v_lshl_add_u64 v[20:21], s[58:59], 0, v[20:21]
	v_lshlrev_b32_e32 v18, 2, v91
	v_lshl_add_u64 v[20:21], v[20:21], 0, v[18:19]
	global_store_dword v[20:21], v26, off
	s_add_u32 s99, s99, 1
; __device__ __forceinline__ float sigmoidf_(float x) { return 1.0f / (1.0f + __expf(-x)); }
; __device__ __forceinline__ f32x4 cv_bf4(const u32x2 w) { return (f32x4){bflo(w.x), bfhi(w.x), bflo(w.y), bfhi(w.y)}; }
; __device__ __forceinline__ void scan_finish(const ScanPtrs& Q, int J, int ci, unsigned char* buf, int ltid, const LStage& L, int toff) {
;     const Job jb = job_decode(J, ci);
;     const int tt = (ltid >> 4) + toff, c = (ltid & 15) * 4;
;     if (tt < jb.nsteps) {
;         const int tok = jb.tok0 + tt; const int tseq = jb.is_s ? tt : ci * SC_CH + tt;
;         const int gc = jb.h * 64 + c;
;         f32x4 r = cv_bf4(L.r), k0 = cv_bf4(L.k), v = cv_bf4(L.v), rp, kp, vp;
;         if (tseq > 0) { rp = cv_bf4(L.rp); kp = cv_bf4(L.kp); vp = cv_bf4(L.vp); }
;         else if (jb.is_s) { rp = L.fr; kp = L.fk; vp = L.fv; }
;         else { rp = (f32x4){0.f, 0.f, 0.f, 0.f}; kp = rp; vp = rp; }
;         const float* mu = Q.mu + gc;
;         r = r + (rp - r) * *(const f32x4*)mu; k0 = k0 + (kp - k0) * *(const f32x4*)(mu + 512); v = v + (vp - v) * *(const f32x4*)(mu + 1024);
;         const f32x4 kk = k0 * *(const f32x4*)(Q.k_k + gc);
;         const float ss = allsum16((kk[0] * kk[0] + kk[1] * kk[1]) + (kk[2] * kk[2] + kk[3] * kk[3]));
;         const float inv = 1.0f / fmaxf(sqrtf(ss), 1e-12f);
;         const f32x4 kkn = kk * inv;
;         const f32x4 dw = cv_bf4(L.sw) + *(const f32x4*)(Q.decay0 + gc);
;         const f32x4 da = cv_bf4(L.sa) + *(const f32x4*)(Q.a0 + gc);
;         f32x4 dec, ain;
; #pragma unroll
;         for (int j = 0; j < 4; ++j) { dec[j] = __expf(-0.60653066f * sigmoidf_(dw[j])); ain[j] = sigmoidf_(da[j]); }
;         const f32x4 ka = *(const f32x4*)(Q.k_a + gc);
;         const f32x4 kf = k0 * (1.0f + (ain - 1.0f) * ka);
;         const f32x4 rkw = *(const f32x4*)(Q.r_k + gc);
;         const f32x4 pr = r * kf * rkw;
.LBB0_492:
	s_or_b64 exec, exec, s[74:75]
	s_nor_b64 s[8:9], s[16:17], s[12:13]
	v_cndmask_b32_e64 v18, 64, 1, s[16:17]
	s_and_saveexec_b64 s[22:23], s[8:9]
	s_cbranch_execz .LBB0_500
	v_cmp_gt_i32_e32 vcc, v120, v104
	v_mov_b32_e32 v48, 0
	v_mov_b32_e32 v49, 0
	v_mov_b32_e32 v50, 0
	v_mov_b32_e32 v51, 0
	v_mov_b32_e32 v52, 0
	v_mov_b32_e32 v92, 0
	v_mov_b32_e32 v53, 0
	v_mov_b32_e32 v93, 0
	v_mov_b32_e32 v44, 0
	v_mov_b32_e32 v45, 0
	v_mov_b32_e32 v46, 0
	v_mov_b32_e32 v47, 0
	s_and_saveexec_b64 s[16:17], vcc
	s_cbranch_execz .LBB0_495
	v_lshlrev_b32_e32 v44, 16, v170
	v_and_b32_e32 v45, 0xffff0000, v170
	v_lshlrev_b32_e32 v46, 16, v171
	v_and_b32_e32 v47, 0xffff0000, v171
	v_lshlrev_b32_e32 v52, 16, v174
	v_and_b32_e32 v92, 0xffff0000, v174
	v_lshlrev_b32_e32 v53, 16, v175
	v_and_b32_e32 v93, 0xffff0000, v175
	v_lshlrev_b32_e32 v48, 16, v182
	v_and_b32_e32 v49, 0xffff0000, v182
	v_lshlrev_b32_e32 v50, 16, v183
	v_and_b32_e32 v51, 0xffff0000, v183
.LBB0_495:
	s_or_b64 exec, exec, s[16:17]
	v_lshl_or_b32 v18, v91, 8, v100
	v_lshlrev_b32_e32 v134, 16, v176
	v_and_b32_e32 v135, 0xffff0000, v176
	v_lshlrev_b32_e32 v136, 16, v177
	v_and_b32_e32 v137, 0xffff0000, v177
	v_sub_f32_e32 v139, v92, v135
	v_sub_f32_e32 v138, v52, v134
	v_sub_f32_e32 v93, v93, v137
	v_sub_f32_e32 v92, v53, v136
	v_lshlrev_b32_e32 v140, 16, v240
	v_and_b32_e32 v141, 0xffff0000, v240
	v_lshlrev_b32_e32 v142, 16, v241
	v_lshlrev_b32_e32 v146, 16, v242
	v_and_b32_e32 v143, 0xffff0000, v241
	v_and_b32_e32 v147, 0xffff0000, v242
	v_lshlrev_b32_e32 v148, 16, v243
	v_and_b32_e32 v149, 0xffff0000, v243
	v_lshlrev_b32_e32 v20, 16, v172
	v_and_b32_e32 v21, 0xffff0000, v172
	v_lshlrev_b32_e32 v42, 16, v173
	v_and_b32_e32 v43, 0xffff0000, v173
	v_sub_f32_e32 v45, v45, v21
	v_sub_f32_e32 v44, v44, v20
	v_sub_f32_e32 v47, v47, v43
	v_sub_f32_e32 v46, v46, v42
	v_pk_fma_f32 v[40:41], v[92:93], v[188:189], v[136:137]
	v_pk_fma_f32 v[38:39], v[138:139], v[186:187], v[134:135]
	v_add_f32_e32 v34, v190, v140
	v_add_f32_e32 v35, v191, v141
	v_pk_mul_f32 v[52:53], v[40:41], v[200:201]
	v_pk_mul_f32 v[92:93], v[38:39], v[198:199]
	v_mul_f32_e32 v124, 0xbfb8aa3b, v34
	v_mul_f32_e32 v125, 0xbfb8aa3b, v35
	v_pk_mul_f32 v[34:35], v[52:53], v[52:53]
	v_pk_mul_f32 v[122:123], v[92:93], v[92:93]
	v_exp_f32_e32 v134, v124
	v_exp_f32_e32 v135, v125
	v_pk_mov_b32 v[124:125], v[122:123], v[34:35] op_sel:[1,0]
	v_mov_b32_e32 v123, v35
	v_pk_add_f32 v[34:35], v[124:125], v[122:123]
	v_add_f32_e32 v123, 1.0, v135
	v_add_f32_e32 v34, v34, v35
	v_add_f32_e32 v35, 1.0, v134
	v_div_scale_f32 v122, s[8:9], v35, v35, 1.0
	v_add_f32_dpp v34, v34, v34 quad_perm:[1,0,3,2] row_mask:0xf bank_mask:0xf bound_ctrl:1
	v_div_scale_f32 v125, s[8:9], v123, v123, 1.0
	s_nop 0
	v_add_f32_dpp v34, v34, v34 quad_perm:[2,3,0,1] row_mask:0xf bank_mask:0xf bound_ctrl:1
	v_rcp_f32_e32 v135, v122
	v_rcp_f32_e32 v136, v125
	v_add_f32_dpp v34, v34, v34 row_half_mirror row_mask:0xf bank_mask:0xf bound_ctrl:1
	v_div_scale_f32 v124, s[16:17], 1.0, v35, 1.0
	s_nop 0
	v_add_f32_dpp v34, v34, v34 row_mirror row_mask:0xf bank_mask:0xf bound_ctrl:1
	v_mul_f32_e32 v137, 0x4f800000, v34
	v_cmp_gt_f32_e32 vcc, s78, v34
	v_fma_f32 v138, -v122, v135, 1.0
	v_fma_f32 v139, -v125, v136, 1.0
	v_cndmask_b32_e32 v34, v34, v137, vcc
	v_sqrt_f32_e32 v137, v34
	v_fmac_f32_e32 v135, v138, v135
	v_div_scale_f32 v134, s[18:19], 1.0, v123, 1.0
	v_fmac_f32_e32 v136, v139, v136
	v_mul_f32_e32 v138, v124, v135
	v_add_f32_e32 v36, v192, v142
	v_mul_f32_e32 v139, v134, v136
	v_fma_f32 v140, -v122, v138, v124
	v_add_u32_e32 v142, -1, v137
	v_add_f32_e32 v30, v194, v146
	v_fma_f32 v141, -v125, v139, v134
	v_add_u32_e32 v146, 1, v137
	v_fmac_f32_e32 v138, v140, v135
	v_fma_f32 v140, -v142, v137, v34
	v_fmac_f32_e32 v139, v141, v136
	v_fma_f32 v141, -v146, v137, v34
	v_cmp_ge_f32_e64 s[20:21], 0, v140
	v_fma_f32 v124, -v122, v138, v124
	v_fma_f32 v125, -v125, v139, v134
	v_cndmask_b32_e64 v122, v137, v142, s[20:21]
	v_cmp_lt_f32_e64 s[20:21], 0, v141
	v_mul_f32_e32 v36, 0xbfb8aa3b, v36
	v_exp_f32_e32 v36, v36
	v_cndmask_b32_e64 v122, v122, v146, s[20:21]
	v_mul_f32_e32 v137, 0x37800000, v122
	v_cndmask_b32_e32 v122, v122, v137, vcc
	v_cmp_class_f32_e32 vcc, v34, v118
	v_add_f32_e32 v36, 1.0, v36
	v_add_f32_e32 v37, v193, v143
	v_cndmask_b32_e32 v34, v122, v34, vcc
	v_max_f32_e32 v34, 0x2b8cbccc, v34
	v_div_scale_f32 v122, s[8:9], v34, v34, -1.0
	v_rcp_f32_e32 v137, v122
	v_div_scale_f32 v134, vcc, -1.0, v34, -1.0
	v_mul_f32_e32 v37, 0xbfb8aa3b, v37
	v_fma_f32 v140, -v122, v137, 1.0
	v_fmac_f32_e32 v137, v140, v137
	v_mul_f32_e32 v140, v134, v137
	v_fma_f32 v141, -v122, v140, v134
	v_fmac_f32_e32 v140, v141, v137
	v_fma_f32 v122, -v122, v140, v134
	v_div_fmas_f32 v122, v122, v137, v140
	s_mov_b64 vcc, s[16:17]
	v_div_fixup_f32 v122, v122, v34, -1.0
	v_div_fmas_f32 v34, v124, v135, v138
	s_mov_b64 vcc, s[18:19]
	v_div_fixup_f32 v34, v34, v35, 1.0
	v_div_fmas_f32 v35, v125, v136, v139
	v_div_fixup_f32 v35, v35, v123, 1.0
	v_div_scale_f32 v123, s[8:9], v36, v36, 1.0
	v_rcp_f32_e32 v124, v123
	v_exp_f32_e32 v37, v37
	v_add_f32_e32 v31, v195, v147
	v_mul_f32_e32 v30, 0xbfb8aa3b, v30
	v_fma_f32 v125, -v123, v124, 1.0
	v_fmac_f32_e32 v124, v125, v124
	v_div_scale_f32 v125, vcc, 1.0, v36, 1.0
	v_mul_f32_e32 v134, v125, v124
	v_fma_f32 v135, -v123, v134, v125
	v_fmac_f32_e32 v134, v135, v124
	v_fma_f32 v123, -v123, v134, v125
	v_div_fmas_f32 v123, v123, v124, v134
	v_add_f32_e32 v37, 1.0, v37
	v_div_fixup_f32 v36, v123, v36, 1.0
; __device__ __forceinline__ float sigmoidf_(float x) { return 1.0f / (1.0f + __expf(-x)); }
; __device__ __forceinline__ f32x4 cv_bf4(const u32x2 w) { return (f32x4){bflo(w.x), bfhi(w.x), bflo(w.y), bfhi(w.y)}; }
; __device__ __forceinline__ void scan_finish(const ScanPtrs& Q, int J, int ci, unsigned char* buf, int ltid, const LStage& L, int toff) {
;     ...
;         const float inv = 1.0f / fmaxf(sqrtf(ss), 1e-12f);
;         const f32x4 kkn = kk * inv;
;         const f32x4 dw = cv_bf4(L.sw) + *(const f32x4*)(Q.decay0 + gc);
;         const f32x4 da = cv_bf4(L.sa) + *(const f32x4*)(Q.a0 + gc);
;         f32x4 dec, ain;
; #pragma unroll
;         for (int j = 0; j < 4; ++j) { dec[j] = __expf(-0.60653066f * sigmoidf_(dw[j])); ain[j] = sigmoidf_(da[j]); }
;         const f32x4 ka = *(const f32x4*)(Q.k_a + gc);
;         const f32x4 kf = k0 * (1.0f + (ain - 1.0f) * ka);
;         const f32x4 rkw = *(const f32x4*)(Q.r_k + gc);
;         const f32x4 pr = r * kf * rkw;
;         const float rk = allsum16((pr[0] + pr[1]) + (pr[2] + pr[3]));
;         unsigned char* tb = buf + tt * SC_TOKB + c * 4;
;         *(f32x4*)(tb) = -kkn; *(f32x4*)(tb + 256) = dec; *(f32x4*)(tb + 512) = kkn * ain; *(f32x4*)(tb + 768) = kf; *(f32x4*)(tb + 1024) = r;
;         if ((c >> 4) == jb.rs) *(f32x4*)(buf + tt * SC_TOKB + 1280 + (c & 15) * 4) = v;
;         if (jb.rs == 0 && c == 0) Q.rk[(size_t)tok * 8 + jb.h] = rk;
	v_div_scale_f32 v123, s[8:9], v37, v37, 1.0
	v_rcp_f32_e32 v124, v123
	v_mul_f32_e32 v31, 0xbfb8aa3b, v31
	v_exp_f32_e32 v30, v30
	v_exp_f32_e32 v31, v31
	v_fma_f32 v125, -v123, v124, 1.0
	v_fmac_f32_e32 v124, v125, v124
	v_div_scale_f32 v125, vcc, 1.0, v37, 1.0
	v_mul_f32_e32 v134, v125, v124
	v_fma_f32 v135, -v123, v134, v125
	v_fmac_f32_e32 v134, v135, v124
	v_fma_f32 v123, -v123, v134, v125
	v_div_fmas_f32 v123, v123, v124, v134
	v_pk_add_f32 v[30:31], v[30:31], 1.0 op_sel_hi:[1,0]
	v_div_fixup_f32 v37, v123, v37, 1.0
	v_div_scale_f32 v123, s[8:9], v31, v31, 1.0
	v_rcp_f32_e32 v124, v123
	v_add_f32_e32 v32, v196, v148
	v_add_f32_e32 v33, v197, v149
	v_mul_f32_e32 v32, 0xbfb8aa3b, v32
	v_fma_f32 v125, -v123, v124, 1.0
	v_fmac_f32_e32 v124, v125, v124
	v_div_scale_f32 v125, vcc, 1.0, v31, 1.0
	v_mul_f32_e32 v134, v125, v124
	v_fma_f32 v135, -v123, v134, v125
	v_fmac_f32_e32 v134, v135, v124
	v_div_scale_f32 v135, s[8:9], v30, v30, 1.0
	v_rcp_f32_e32 v136, v135
	v_mul_f32_e32 v33, 0xbfb8aa3b, v33
	v_fma_f32 v123, -v123, v134, v125
	v_exp_f32_e32 v32, v32
	v_exp_f32_e32 v33, v33
	v_div_fmas_f32 v123, v123, v124, v134
	v_div_fixup_f32 v125, v123, v31, 1.0
	v_fma_f32 v31, -v135, v136, 1.0
	v_fmac_f32_e32 v136, v31, v136
	v_div_scale_f32 v31, vcc, 1.0, v30, 1.0
	v_mul_f32_e32 v123, v31, v136
	v_pk_add_f32 v[32:33], v[32:33], 1.0 op_sel_hi:[1,0]
	v_fma_f32 v124, -v135, v123, v31
	v_fmac_f32_e32 v123, v124, v136
	v_div_scale_f32 v134, s[8:9], v33, v33, 1.0
	v_fma_f32 v31, -v135, v123, v31
	v_rcp_f32_e32 v135, v134
	v_div_fmas_f32 v31, v31, v136, v123
	v_div_fixup_f32 v124, v31, v30, 1.0
	v_mul_f32_e32 v34, 0xbf1b4598, v34
	v_fma_f32 v30, -v134, v135, 1.0
	v_fmac_f32_e32 v135, v30, v135
	v_div_scale_f32 v30, vcc, 1.0, v33, 1.0
	v_mul_f32_e32 v31, v30, v135
	v_fma_f32 v123, -v134, v31, v30
	v_fmac_f32_e32 v31, v123, v135
	v_div_scale_f32 v123, s[8:9], v32, v32, 1.0
	v_fma_f32 v30, -v134, v31, v30
	v_rcp_f32_e32 v134, v123
	v_div_fmas_f32 v30, v30, v135, v31
	v_div_fixup_f32 v33, v30, v33, 1.0
	v_mul_f32_e32 v35, 0xbf1b4598, v35
	v_fma_f32 v30, -v123, v134, 1.0
	v_fmac_f32_e32 v134, v30, v134
	v_div_scale_f32 v30, vcc, 1.0, v32, 1.0
	v_mul_f32_e32 v31, v30, v134
	v_fma_f32 v135, -v123, v31, v30
	v_fmac_f32_e32 v31, v135, v134
	v_fma_f32 v30, -v123, v31, v30
	v_div_fmas_f32 v30, v30, v134, v31
	v_div_fixup_f32 v32, v30, v32, 1.0
	v_pk_fma_f32 v[30:31], v[46:47], v[204:205], v[42:43]
	v_pk_fma_f32 v[28:29], v[44:45], v[202:203], v[20:21]
	v_pk_add_f32 v[20:21], v[32:33], -1.0 op_sel_hi:[1,0]
	v_pk_add_f32 v[26:27], v[124:125], -1.0 op_sel_hi:[1,0]
	v_pk_fma_f32 v[20:21], v[208:209], v[20:21], 1.0 op_sel_hi:[1,1,0]
	v_pk_fma_f32 v[26:27], v[206:207], v[26:27], 1.0 op_sel_hi:[1,1,0]
	v_pk_mul_f32 v[40:41], v[40:41], v[20:21]
	v_pk_mul_f32 v[38:39], v[38:39], v[26:27]
	v_pk_mul_f32 v[26:27], v[30:31], v[40:41]
	v_pk_mul_f32 v[20:21], v[28:29], v[38:39]
	v_pk_mul_f32 v[26:27], v[212:213], v[26:27]
	v_pk_mul_f32 v[20:21], v[210:211], v[20:21]
	v_mul_f32_e32 v36, 0xbf1b4598, v36
	v_mul_f32_e32 v37, 0xbf1b4598, v37
	v_add_f32_e32 v20, v20, v21
	v_add_f32_e32 v21, v26, v27
	v_mul_f32_e32 v34, 0x3fb8aa3b, v34
	v_mul_f32_e32 v35, 0x3fb8aa3b, v35
	v_mul_f32_e32 v36, 0x3fb8aa3b, v36
	v_mul_f32_e32 v37, 0x3fb8aa3b, v37
	v_add_f32_e32 v20, v20, v21
	v_exp_f32_e32 v34, v34
	v_exp_f32_e32 v35, v35
	v_exp_f32_e32 v36, v36
	v_exp_f32_e32 v37, v37
	v_add_f32_dpp v20, v20, v20 quad_perm:[1,0,3,2] row_mask:0xf bank_mask:0xf bound_ctrl:1
	v_add_u32_e32 v26, s6, v105
	v_mov_b32_e32 v21, 0
	v_add_f32_dpp v20, v20, v20 quad_perm:[2,3,0,1] row_mask:0xf bank_mask:0xf bound_ctrl:1
	v_add_u32_e32 v27, v26, v100
	v_pk_mul_f32 v[44:45], v[52:53], v[122:123] op_sel_hi:[1,0]
	v_add_f32_dpp v20, v20, v20 row_half_mirror row_mask:0xf bank_mask:0xf bound_ctrl:1
	v_pk_mul_f32 v[42:43], v[92:93], v[122:123] op_sel_hi:[1,0]
	ds_write_b128 v27, v[42:45]
	ds_write_b128 v27, v[34:37] offset:256
	v_mov_b32_dpp v21, v20 row_mirror row_mask:0xf bank_mask:0xf
	v_pk_mul_f32 v[34:35], v[44:45], v[32:33] neg_lo:[1,0] neg_hi:[1,0]
	v_pk_mul_f32 v[32:33], v[42:43], v[124:125] neg_lo:[1,0] neg_hi:[1,0]
	v_cmp_eq_u32_e32 vcc, v101, v121
	ds_write_b128 v27, v[32:35] offset:512
	ds_write_b128 v27, v[38:41] offset:768
	ds_write_b128 v27, v[28:31] offset:1024
	s_and_saveexec_b64 s[16:17], vcc
	s_cbranch_execz .LBB0_497
	v_lshl_add_u64 v[28:29], s[30:31], 0, v[18:19]
	v_add_co_u32_e32 v28, vcc, 0x1000, v28
	v_lshlrev_b32_e32 v32, 16, v184
	s_nop 0
	v_addc_co_u32_e32 v29, vcc, 0, v29, vcc
	v_and_b32_e32 v33, 0xffff0000, v184
	v_lshlrev_b32_e32 v34, 16, v185
	v_and_b32_e32 v35, 0xffff0000, v185
	v_add_u32_e32 v18, v26, v102
	v_sub_f32_e32 v37, v51, v35
	v_sub_f32_e32 v36, v50, v34
	v_sub_f32_e32 v27, v49, v33
	v_sub_f32_e32 v26, v48, v32
	v_pk_fma_f32 v[26:27], v[26:27], v[214:215], v[32:33]
	v_pk_fma_f32 v[28:29], v[36:37], v[216:217], v[34:35]
	ds_write_b128 v18, v[26:29] offset:1280
.LBB0_497:
	s_or_b64 exec, exec, s[16:17]
	v_or_b32_e32 v18, v121, v97
	v_cmp_eq_u32_e32 vcc, 0, v18
	s_and_saveexec_b64 s[16:17], vcc
	s_cbranch_execz .LBB0_499
	v_lshlrev_b32_e32 v18, 6, v94
	v_and_b32_e32 v18, 0xfffff800, v18
	v_add_u32_e32 v18, v18, v120
	v_add_f32_e32 v26, v20, v21
	v_or_b32_e32 v20, v18, v103
	v_ashrrev_i32_e32 v21, 31, v20
	v_lshlrev_b64 v[20:21], 5, v[20:21]
	v_lshl_add_u64 v[20:21], s[58:59], 0, v[20:21]
	v_lshlrev_b32_e32 v18, 2, v91
	v_lshl_add_u64 v[20:21], v[20:21], 0, v[18:19]
	global_store_dword v[20:21], v26, off
	s_add_u32 s99, s99, 1

; #define SC_ADV(J_, c_) do { if ((J_) < NJOBS) { if (++(c_) >= ((J_) < 256 ? SEQ / SC_CH : 1)) { (J_) += G; (c_) = 0; } } } while (0)
; __device__ void phase_scan(int l, unsigned char* lds) {
;     ...
;             if (Jg < NJOBS) { scan_finish(Q, Jg, cg_, lds + ((it + 2) % 3) * SC_BUFB, tid - 256, L, 0); scan_finish(Q, Jg, cg_, lds + ((it + 2) % 3) * SC_BUFB, tid - 256, L2, 16); }
;             SC_ADV(Jg, cg_);
;             if (Ji < NJOBS) { scan_issue(Q, Ji, cis, tid - 256, L, 0); scan_issue(Q, Ji, cis, tid - 256, L2, 16); }
;             SC_ADV(Ji, cis);
.LBB0_501:
	s_or_b64 exec, exec, s[72:73]
.LBB0_522:
	s_or_saveexec_b64 s[16:17], s[70:71]
	s_add_i32 s6, s85, s51
	s_xor_b64 exec, exec, s[16:17]
	s_cbranch_execz .LBB0_474
	s_mov_b64 s[20:21], -1
	s_and_b64 vcc, exec, s[68:69]
	s_cbranch_vccz .LBB0_525
	s_add_i32 s7, s51, 0xffffff00
	s_lshr_b32 s18, s7, 5
	s_lshl_b32 s7, s18, 3
	s_addk_i32 s7, 0x4000
	s_mov_b64 s[20:21], 0

; #define KP(f) ((decltype(Params::f))karg_ptr<(int)offsetof(Params, f)>())
; __device__ void phase_scan(int l, unsigned char* lds) {
;     int tid_ = threadIdx.x; asm volatile("" : "+v"(tid_));
;     const int tid = tid_, wid = tid >> 6, lane = tid & 63, G = gridDim.x;
;     const bool loader = wid >= 4;
;     if (!loader) __builtin_amdgcn_s_setprio(3);
;     ScanPtrs Q;
;     Q.z = KP(z); Q.sw = KP(xb) + (size_t)T_ALL * 512; Q.sa = KP(sc_a); Q.st_shift = KP(state_shift) + (size_t)l * NSB * DSH; Q.mu = KP(mu_shift) + (size_t)l * DSH;
;     Q.k_k = KP(k_k) + (size_t)l * 512; Q.k_a = KP(k_a) + (size_t)l * 512; Q.r_k = KP(r_k) + (size_t)l * 512; Q.decay0 = KP(decay0) + (size_t)l * 512; Q.a0 = KP(a0) + (size_t)l * 512; Q.rk = KP(rk);
;     bf16_t* ybuf = KP(xb);
;     const float* st_wkv = KP(state_wkv); float* out = KP(out);
;     int J = (G % 8 == 0) ? (int)(blockIdx.x % 8) * (G / 8) + (int)(blockIdx.x / 8) : (int)blockIdx.x, ci = 0, it = 0;
.LBB0_1542:
	s_or_b64 exec, exec, s[10:11]
	s_mov_b32 s6, s2
	s_mov_b32 s7, s46
	v_mov_b32_e32 v53, v166
	s_waitcnt lgkmcnt(0)
	s_barrier
	s_nop 0
	v_ashrrev_i32_e32 v52, 6, v53
	s_mov_b32 s98, -1
	s_mov_b32 s99, 0
	v_cmp_lt_i32_e64 s[10:11], 3, v52
	v_cmp_gt_i32_e64 s[12:13], 4, v52
	s_and_saveexec_b64 s[14:15], s[12:13]
	s_setprio 3
	s_or_b64 exec, exec, s[14:15]
	s_load_dwordx2 s[22:23], s[0:1], 0x130
	s_waitcnt lgkmcnt(0)
	s_load_dwordx2 s[16:17], s[0:1], 0x120
	s_waitcnt lgkmcnt(0)
	s_load_dwordx2 s[24:25], s[0:1], 0x140
	s_waitcnt lgkmcnt(0)
	s_load_dwordx2 s[18:19], s[0:1], 16
	s_waitcnt lgkmcnt(0)
	s_load_dwordx2 s[14:15], s[0:1], 56
	s_waitcnt lgkmcnt(0)
	s_load_dwordx2 s[26:27], s[0:1], 0x68
	s_waitcnt lgkmcnt(0)
	s_load_dwordx2 s[28:29], s[0:1], 0x70
	s_waitcnt lgkmcnt(0)
	s_load_dwordx2 s[30:31], s[0:1], 0x78
	s_waitcnt lgkmcnt(0)
	s_load_dwordx2 s[34:35], s[0:1], 64
	s_waitcnt lgkmcnt(0)
	s_load_dwordx2 s[36:37], s[0:1], 0x50
	s_waitcnt lgkmcnt(0)
	s_load_dwordx2 s[38:39], s[0:1], 0x150
	s_waitcnt lgkmcnt(0)
	s_load_dwordx2 s[40:41], s[0:1], 0x120
	s_waitcnt lgkmcnt(0)
	s_load_dwordx2 s[20:21], s[0:1], 32
	s_waitcnt lgkmcnt(0)
	s_load_dwordx2 s[42:43], s[0:1], 0xd8
	s_waitcnt lgkmcnt(0)
	v_readlane_b32 s6, v230, 6
	v_readlane_b32 s7, v230, 7
	s_and_b64 vcc, exec, s[6:7]
	s_mov_b32 s53, s2
	s_cbranch_vccnz .LBB0_1546
	s_and_b32 s6, s2, 7
	s_ashr_i32 s7, s46, 3
	s_mul_i32 s6, s7, s6
	s_lshr_b32 s7, s2, 3
	s_add_i32 s53, s6, s7

; #define SC_ADV(J_, c_) do { if ((J_) < NJOBS) { if (++(c_) >= ((J_) < 256 ? SEQ / SC_CH : 1)) { (J_) += G; (c_) = 0; } } } while (0)
; __device__ void phase_scan(int l, unsigned char* lds) {
;     ...
;         int Jn = J, cn = ci; SC_ADV(Jn, cn);
;     ...
;         if (loader) {
.LBB0_1616:
	s_add_i32 s14, s60, 1
	s_cmpk_gt_i32 s53, 0xff
	s_cselect_b64 s[66:67], -1, 0
	s_cmpk_lt_i32 s53, 0x100
	s_cselect_b64 s[62:63], -1, 0
	s_and_b64 s[6:7], s[62:63], exec
	s_cselect_b32 s6, 64, 1
	s_cmp_lt_i32 s14, s6
	s_cselect_b64 s[64:65], -1, 0
	s_and_b64 s[6:7], s[64:65], exec
	s_cselect_b32 s85, s14, 0
	s_cselect_b32 s86, 0, s46
	s_and_saveexec_b64 s[6:7], s[10:11]
	s_xor_b64 s[68:69], exec, s[6:7]
	s_cbranch_execz .LBB0_1663
	s_cmp_lg_u32 s99, 0
	s_cbranch_scc1 .Lld_w1_1
	s_waitcnt vmcnt(0)
	s_branch .Lld_wd_1

; __device__ __forceinline__ void scan_issue(const ScanPtrs& Q, int J, int ci, int ltid, LStage& L, int toff) {
;     const Job jb = job_decode(J, ci);
;     const int tt = (ltid >> 4) + toff, c = (ltid & 15) * 4;
;     if (tt < jb.nsteps) {
;         const int tok = jb.tok0 + tt; const int tseq = jb.is_s ? tt : ci * SC_CH + tt;
;         const int gc = jb.h * 64 + c;
;         const bf16_t* zr = Q.z + (size_t)tok * DIN + gc;
;         L.r = *(const u32x2*)zr; L.k = *(const u32x2*)(zr + 512); L.v = *(const u32x2*)(zr + 1024);
;         if (tseq > 0) { L.rp = *(const u32x2*)(zr - DIN); L.kp = *(const u32x2*)(zr - DIN + 512); L.vp = *(const u32x2*)(zr - DIN + 1024); }
;         else if (jb.is_s) { const float* sp = Q.st_shift + (size_t)jb.seq * DSH + gc; L.fr = *(const f32x4*)sp; L.fk = *(const f32x4*)(sp + 512); L.fv = *(const f32x4*)(sp + 1024); }
;         L.sw = *(const u32x2*)(Q.sw + (size_t)tok * 512 + gc); L.sa = *(const u32x2*)(Q.sa + (size_t)tok * 512 + gc);
;     }
.Lld_wd_1:
	s_mov_b32 s99, 0
	v_mov_b64_e32 v[218:219], v[6:7]
	v_mov_b64_e32 v[220:221], v[8:9]
	v_mov_b64_e32 v[222:223], v[10:11]
	v_mov_b64_e32 v[224:225], v[12:13]
	v_mov_b64_e32 v[226:227], v[14:15]
	v_mov_b64_e32 v[228:229], v[16:17]
	v_mov_b64_e32 v[170:171], v[54:55]
	v_mov_b64_e32 v[172:173], v[56:57]
	v_mov_b64_e32 v[174:175], v[58:59]
	v_mov_b64_e32 v[176:177], v[60:61]
	v_mov_b64_e32 v[178:179], v[62:63]
	v_mov_b64_e32 v[180:181], v[64:65]
	v_mov_b64_e32 v[182:183], v[66:67]
	v_mov_b64_e32 v[184:185], v[68:69]
	v_mov_b64_e32 v[232:233], v[70:71]
	v_mov_b64_e32 v[234:235], v[72:73]
	v_mov_b64_e32 v[236:237], v[74:75]
	v_mov_b64_e32 v[238:239], v[76:77]
	v_mov_b64_e32 v[240:241], v[78:79]
	v_mov_b64_e32 v[242:243], v[80:81]
	v_mov_b64_e32 v[244:245], v[82:83]
	v_mov_b64_e32 v[246:247], v[84:85]
	v_cmp_gt_i32_e32 vcc, s76, v1
	s_and_saveexec_b64 s[18:19], vcc
	s_cbranch_execz .LBB0_1662
	v_cmp_lt_i32_e32 vcc, s74, v1
	v_cmp_gt_i32_e64 s[14:15], s75, v1
	s_and_saveexec_b64 s[6:7], s[14:15]
	s_xor_b64 s[16:17], exec, s[6:7]
	s_cbranch_execz .LBB0_1653
	v_ashrrev_i32_e32 v21, 5, v1
	v_lshlrev_b32_e32 v18, 5, v0
	v_lshl_add_u32 v18, v21, 11, v18
	s_or_saveexec_b64 s[16:17], s[16:17]
	v_mov_b32_e32 v20, 32
	s_xor_b64 exec, exec, s[16:17]
	s_cbranch_execnz .LBB0_1654

; __device__ __forceinline__ f32x4 cv_bf4(const u32x2 w) { return (f32x4){bflo(w.x), bfhi(w.x), bflo(w.y), bfhi(w.y)}; }
; __device__ __forceinline__ void scan_finish(const ScanPtrs& Q, int J, int ci, unsigned char* buf, int ltid, const LStage& L, int toff) {
;     const Job jb = job_decode(J, ci);
;     const int tt = (ltid >> 4) + toff, c = (ltid & 15) * 4;
;     if (tt < jb.nsteps) {
;         const int tok = jb.tok0 + tt; const int tseq = jb.is_s ? tt : ci * SC_CH + tt;
;         const int gc = jb.h * 64 + c;
;         f32x4 r = cv_bf4(L.r), k0 = cv_bf4(L.k), v = cv_bf4(L.v), rp, kp, vp;
;         if (tseq > 0) { rp = cv_bf4(L.rp); kp = cv_bf4(L.kp); vp = cv_bf4(L.vp); }
;         else if (jb.is_s) { rp = L.fr; kp = L.fk; vp = L.fv; }
;         else { rp = (f32x4){0.f, 0.f, 0.f, 0.f}; kp = rp; vp = rp; }
.LBB0_1662:
	s_or_b64 exec, exec, s[18:19]
	v_cmp_gt_i32_e32 vcc, s76, v94
	s_and_saveexec_b64 s[70:71], vcc
	s_cbranch_execz .LBB0_1642
	v_cmp_lt_i32_e64 s[14:15], s74, v94
	v_cmp_gt_i32_e32 vcc, s75, v94
	s_and_saveexec_b64 s[6:7], vcc
	s_xor_b64 s[16:17], exec, s[6:7]
	v_lshlrev_b32_e32 v18, 6, v94
	v_and_b32_e32 v18, 0xfffff800, v18
	v_lshl_add_u32 v122, v95, 5, v18
	s_or_saveexec_b64 s[16:17], s[16:17]
	v_mov_b32_e32 v18, 32
	s_xor_b64 exec, exec, s[16:17]
	v_add_u32_e32 v18, 0xffffff00, v94
	v_lshrrev_b32_e32 v18, 2, v18
	v_and_b32_e32 v18, 0x3ffffff8, v18
	v_add_u32_e32 v122, 0x4000, v18
	v_mov_b32_e32 v18, 8
	s_or_b64 exec, exec, s[16:17]
	s_add_i32 s6, s84, 2
	s_mul_hi_u32 s7, s6, 0xaaaaaaab
	s_lshr_b32 s7, s7, 1
	s_mul_i32 s7, s7, 3
	s_sub_i32 s6, s6, s7
	s_mul_i32 s6, s6, 0xa800
	s_add_i32 s6, s6, 0
	v_and_b32_e32 v121, 3, v94
	v_bfe_u32 v91, v94, 2, 3
	v_cmp_lt_u32_e32 vcc, v96, v18
	v_lshlrev_b32_e32 v120, 5, v95
	s_and_saveexec_b64 s[72:73], vcc
	s_cbranch_execz .LBB0_1633
	v_cndmask_b32_e64 v18, v120, 0, s[14:15]
	v_cmp_le_i32_e32 vcc, v18, v98
	s_and_saveexec_b64 s[16:17], vcc
	s_xor_b64 s[16:17], exec, s[16:17]
	s_cbranch_execz .LBB0_1627
	v_mov_b32_e32 v20, v19
	v_mov_b32_e32 v21, v19
	v_mov_b32_e32 v18, v19
	v_mov_b64_e32 v[48:49], v[20:21]
	v_mov_b64_e32 v[52:53], v[20:21]
	v_mov_b64_e32 v[28:29], v[20:21]
	v_mov_b64_e32 v[46:47], v[18:19]
	v_mov_b64_e32 v[50:51], v[18:19]
	v_mov_b64_e32 v[26:27], v[18:19]
	s_and_saveexec_b64 s[18:19], s[14:15]
	s_cbranch_execz .LBB0_1626
	v_mov_b64_e32 v[48:49], v[220:221]
	v_mov_b64_e32 v[52:53], v[224:225]
	v_mov_b64_e32 v[28:29], v[228:229]
	v_mov_b64_e32 v[46:47], v[218:219]
	v_mov_b64_e32 v[50:51], v[222:223]
	v_mov_b64_e32 v[26:27], v[226:227]

; __device__ __forceinline__ float sigmoidf_(float x) { return 1.0f / (1.0f + __expf(-x)); }
; __device__ __forceinline__ f32x4 cv_bf4(const u32x2 w) { return (f32x4){bflo(w.x), bfhi(w.x), bflo(w.y), bfhi(w.y)}; }
; __device__ __forceinline__ void scan_finish(const ScanPtrs& Q, int J, int ci, unsigned char* buf, int ltid, const LStage& L, int toff) {
;     ...
;         f32x4 r = cv_bf4(L.r), k0 = cv_bf4(L.k), v = cv_bf4(L.v), rp, kp, vp;
;         if (tseq > 0) { rp = cv_bf4(L.rp); kp = cv_bf4(L.kp); vp = cv_bf4(L.vp); }
;         else if (jb.is_s) { rp = L.fr; kp = L.fk; vp = L.fv; }
;         else { rp = (f32x4){0.f, 0.f, 0.f, 0.f}; kp = rp; vp = rp; }
;         const float* mu = Q.mu + gc;
;         r = r + (rp - r) * *(const f32x4*)mu; k0 = k0 + (kp - k0) * *(const f32x4*)(mu + 512); v = v + (vp - v) * *(const f32x4*)(mu + 1024);
;         const f32x4 kk = k0 * *(const f32x4*)(Q.k_k + gc);
;         const float ss = allsum16((kk[0] * kk[0] + kk[1] * kk[1]) + (kk[2] * kk[2] + kk[3] * kk[3]));
;         const float inv = 1.0f / fmaxf(sqrtf(ss), 1e-12f);
;         const f32x4 kkn = kk * inv;
;         const f32x4 dw = cv_bf4(L.sw) + *(const f32x4*)(Q.decay0 + gc);
;         const f32x4 da = cv_bf4(L.sa) + *(const f32x4*)(Q.a0 + gc);
;         f32x4 dec, ain;
; #pragma unroll
;         for (int j = 0; j < 4; ++j) { dec[j] = __expf(-0.60653066f * sigmoidf_(dw[j])); ain[j] = sigmoidf_(da[j]); }
;         const f32x4 ka = *(const f32x4*)(Q.k_a + gc);
;         const f32x4 kf = k0 * (1.0f + (ain - 1.0f) * ka);
;         const f32x4 rkw = *(const f32x4*)(Q.r_k + gc);
;         const f32x4 pr = r * kf * rkw;
;         const float rk = allsum16((pr[0] + pr[1]) + (pr[2] + pr[3]));
.LBB0_1627:
	s_andn2_saveexec_b64 s[16:17], s[16:17]
	s_cbranch_execz .LBB0_1629
	v_lshlrev_b32_e32 v46, 16, v180
	v_and_b32_e32 v47, 0xffff0000, v180
	v_lshlrev_b32_e32 v48, 16, v181
	v_and_b32_e32 v49, 0xffff0000, v181
	v_lshlrev_b32_e32 v50, 16, v236
	v_and_b32_e32 v51, 0xffff0000, v236
	v_lshlrev_b32_e32 v52, 16, v237
	v_and_b32_e32 v53, 0xffff0000, v237
	v_lshlrev_b32_e32 v26, 16, v238
	v_and_b32_e32 v27, 0xffff0000, v238
	v_lshlrev_b32_e32 v28, 16, v239
	v_and_b32_e32 v29, 0xffff0000, v239
.LBB0_1629:
	s_or_b64 exec, exec, s[16:17]
	v_lshl_or_b32 v18, v91, 8, v100
	v_readfirstlane_b32 s100, v91
	s_nop 3
	s_cmp_eq_u32 s100, s98
	s_cbranch_scc1 .Lprm_ok_1
	s_mov_b32 s98, s100
	s_lshl_b32 s100, s100, 8
	v_or_b32_e32 v251, s100, v100
	global_load_dwordx4 v[186:189], v251, s[58:59] offset:2048
	global_load_dwordx4 v[190:193], v251, s[34:35] offset:2048
	global_load_dwordx4 v[194:197], v251, s[36:37] offset:2048
	global_load_dwordx4 v[198:201], v251, s[26:27] offset:2048
	global_load_dwordx4 v[202:205], v251, s[58:59]
	global_load_dwordx4 v[206:209], v251, s[28:29] offset:2048
	global_load_dwordx4 v[210:213], v251, s[30:31] offset:2048
	v_add_u32_e32 v250, 0x1000, v251
	global_load_dwordx4 v[214:217], v250, s[58:59]
	s_waitcnt vmcnt(0)
.Lprm_ok_1:
	v_lshlrev_b32_e32 v132, 16, v232
	v_and_b32_e32 v133, 0xffff0000, v232
	v_lshlrev_b32_e32 v134, 16, v233
	v_and_b32_e32 v135, 0xffff0000, v233
	v_sub_f32_e32 v137, v51, v133
	v_sub_f32_e32 v136, v50, v132
	v_sub_f32_e32 v139, v53, v135
	v_sub_f32_e32 v138, v52, v134
	v_lshlrev_b32_e32 v123, 16, v244
	v_and_b32_e32 v140, 0xffff0000, v244
	v_lshlrev_b32_e32 v141, 16, v245
	v_lshlrev_b32_e32 v143, 16, v246
	v_and_b32_e32 v142, 0xffff0000, v245
	v_and_b32_e32 v146, 0xffff0000, v246
	v_lshlrev_b32_e32 v147, 16, v247
	v_and_b32_e32 v148, 0xffff0000, v247
	v_lshlrev_b32_e32 v20, 16, v178
	v_and_b32_e32 v21, 0xffff0000, v178
	v_lshlrev_b32_e32 v92, 16, v179
	v_and_b32_e32 v93, 0xffff0000, v179
	v_sub_f32_e32 v47, v47, v21
	v_sub_f32_e32 v46, v46, v20
	v_sub_f32_e32 v49, v49, v93
	v_sub_f32_e32 v48, v48, v92
	v_pk_fma_f32 v[44:45], v[138:139], v[188:189], v[134:135]
	v_pk_fma_f32 v[42:43], v[136:137], v[186:187], v[132:133]
	v_add_f32_e32 v38, v190, v123
	v_add_f32_e32 v39, v191, v140
	v_pk_mul_f32 v[126:127], v[44:45], v[200:201]
	v_pk_mul_f32 v[124:125], v[42:43], v[198:199]
	v_mul_f32_e32 v123, 0xbfb8aa3b, v38
	v_mul_f32_e32 v134, 0xbfb8aa3b, v39
	v_pk_mul_f32 v[38:39], v[126:127], v[126:127]
	v_pk_mul_f32 v[132:133], v[124:125], v[124:125]
	v_exp_f32_e32 v123, v123
	v_exp_f32_e32 v136, v134
	v_pk_mov_b32 v[134:135], v[132:133], v[38:39] op_sel:[1,0]
	v_mov_b32_e32 v133, v39
	v_pk_add_f32 v[38:39], v[134:135], v[132:133]
	v_add_f32_e32 v40, v192, v141
	v_add_f32_e32 v38, v38, v39
	v_add_f32_e32 v39, 1.0, v123
	v_add_f32_e32 v123, 1.0, v136
	v_add_f32_dpp v38, v38, v38 quad_perm:[1,0,3,2] row_mask:0xf bank_mask:0xf bound_ctrl:1
	v_div_scale_f32 v132, s[16:17], v39, v39, 1.0
	s_nop 0
	v_add_f32_dpp v38, v38, v38 quad_perm:[2,3,0,1] row_mask:0xf bank_mask:0xf bound_ctrl:1
	v_div_scale_f32 v134, s[18:19], v123, v123, 1.0
	s_nop 0
	v_add_f32_dpp v38, v38, v38 row_half_mirror row_mask:0xf bank_mask:0xf bound_ctrl:1
	v_rcp_f32_e32 v136, v132
	v_rcp_f32_e32 v137, v134
	v_add_f32_dpp v38, v38, v38 row_mirror row_mask:0xf bank_mask:0xf bound_ctrl:1
	v_mul_f32_e32 v138, 0x4f800000, v38
	v_cmp_gt_f32_e32 vcc, s77, v38
	v_fma_f32 v139, -v132, v136, 1.0
	v_div_scale_f32 v133, s[16:17], 1.0, v39, 1.0
	v_cndmask_b32_e32 v38, v38, v138, vcc
	v_sqrt_f32_e32 v138, v38
	v_fma_f32 v140, -v134, v137, 1.0
	v_fmac_f32_e32 v136, v139, v136
	v_div_scale_f32 v135, s[18:19], 1.0, v123, 1.0
	v_fmac_f32_e32 v137, v140, v137
	v_mul_f32_e32 v139, v133, v136
	v_mul_f32_e32 v140, v135, v137
	v_fma_f32 v141, -v132, v139, v133
	v_add_u32_e32 v149, -1, v138
	v_add_f32_e32 v34, v194, v143
	v_fma_f32 v143, -v134, v140, v135
	v_add_u32_e32 v150, 1, v138
	v_fmac_f32_e32 v139, v141, v136
	v_fma_f32 v141, -v149, v138, v38
	v_fmac_f32_e32 v140, v143, v137
	v_fma_f32 v143, -v150, v138, v38
	v_cmp_ge_f32_e64 s[20:21], 0, v141
	v_fma_f32 v133, -v132, v139, v133
	v_fma_f32 v134, -v134, v140, v135
	v_cndmask_b32_e64 v132, v138, v149, s[20:21]
	v_cmp_lt_f32_e64 s[20:21], 0, v143
	v_mul_f32_e32 v40, 0xbfb8aa3b, v40
	v_exp_f32_e32 v40, v40
	v_cndmask_b32_e64 v132, v132, v150, s[20:21]
	v_mul_f32_e32 v138, 0x37800000, v132
	v_cndmask_b32_e32 v132, v132, v138, vcc
	v_cmp_class_f32_e32 vcc, v38, v118
	v_add_f32_e32 v40, 1.0, v40
	v_add_f32_e32 v41, v193, v142
	v_cndmask_b32_e32 v38, v132, v38, vcc
	v_max_f32_e32 v38, 0x2b8cbccc, v38
	v_div_scale_f32 v132, s[20:21], v38, v38, -1.0
	v_rcp_f32_e32 v138, v132
	v_div_scale_f32 v135, vcc, -1.0, v38, -1.0
	v_mul_f32_e32 v41, 0xbfb8aa3b, v41
	v_fma_f32 v141, -v132, v138, 1.0
	v_fmac_f32_e32 v138, v141, v138
	v_mul_f32_e32 v141, v135, v138
	v_fma_f32 v143, -v132, v141, v135
	v_fmac_f32_e32 v141, v143, v138
	v_fma_f32 v132, -v132, v141, v135
	v_div_fmas_f32 v132, v132, v138, v141
	s_mov_b64 vcc, s[16:17]
	v_div_fixup_f32 v132, v132, v38, -1.0
	v_div_fmas_f32 v38, v133, v136, v139
	s_mov_b64 vcc, s[18:19]
	v_div_fixup_f32 v38, v38, v39, 1.0
	v_div_fmas_f32 v39, v134, v137, v140
	v_div_fixup_f32 v39, v39, v123, 1.0
	v_div_scale_f32 v123, s[16:17], v40, v40, 1.0
	v_rcp_f32_e32 v133, v123
	v_exp_f32_e32 v41, v41
	v_add_f32_e32 v35, v195, v146
	v_mul_f32_e32 v34, 0xbfb8aa3b, v34
	v_fma_f32 v134, -v123, v133, 1.0
	v_fmac_f32_e32 v133, v134, v133
	v_div_scale_f32 v134, vcc, 1.0, v40, 1.0
	v_mul_f32_e32 v135, v134, v133
	v_fma_f32 v136, -v123, v135, v134
	v_fmac_f32_e32 v135, v136, v133
	v_fma_f32 v123, -v123, v135, v134
; __device__ __forceinline__ float sigmoidf_(float x) { return 1.0f / (1.0f + __expf(-x)); }
; __device__ __forceinline__ f32x4 cv_bf4(const u32x2 w) { return (f32x4){bflo(w.x), bfhi(w.x), bflo(w.y), bfhi(w.y)}; }
; __device__ __forceinline__ void scan_finish(const ScanPtrs& Q, int J, int ci, unsigned char* buf, int ltid, const LStage& L, int toff) {
;     ...
;         const f32x4 dw = cv_bf4(L.sw) + *(const f32x4*)(Q.decay0 + gc);
;         const f32x4 da = cv_bf4(L.sa) + *(const f32x4*)(Q.a0 + gc);
;         f32x4 dec, ain;
; #pragma unroll
;         for (int j = 0; j < 4; ++j) { dec[j] = __expf(-0.60653066f * sigmoidf_(dw[j])); ain[j] = sigmoidf_(da[j]); }
;         const f32x4 ka = *(const f32x4*)(Q.k_a + gc);
;         const f32x4 kf = k0 * (1.0f + (ain - 1.0f) * ka);
;         const f32x4 rkw = *(const f32x4*)(Q.r_k + gc);
;         const f32x4 pr = r * kf * rkw;
;         const float rk = allsum16((pr[0] + pr[1]) + (pr[2] + pr[3]));
;         unsigned char* tb = buf + tt * SC_TOKB + c * 4;
;         *(f32x4*)(tb) = -kkn; *(f32x4*)(tb + 256) = dec; *(f32x4*)(tb + 512) = kkn * ain; *(f32x4*)(tb + 768) = kf; *(f32x4*)(tb + 1024) = r;
;         if ((c >> 4) == jb.rs) *(f32x4*)(buf + tt * SC_TOKB + 1280 + (c & 15) * 4) = v;
;         if (jb.rs == 0 && c == 0) Q.rk[(size_t)tok * 8 + jb.h] = rk;
	v_div_fmas_f32 v123, v123, v133, v135
	v_add_f32_e32 v41, 1.0, v41
	v_div_fixup_f32 v40, v123, v40, 1.0
	v_div_scale_f32 v123, s[16:17], v41, v41, 1.0
	v_rcp_f32_e32 v133, v123
	v_mul_f32_e32 v35, 0xbfb8aa3b, v35
	v_exp_f32_e32 v34, v34
	v_exp_f32_e32 v35, v35
	v_fma_f32 v134, -v123, v133, 1.0
	v_fmac_f32_e32 v133, v134, v133
	v_div_scale_f32 v134, vcc, 1.0, v41, 1.0
	v_mul_f32_e32 v135, v134, v133
	v_fma_f32 v136, -v123, v135, v134
	v_fmac_f32_e32 v135, v136, v133
	v_fma_f32 v123, -v123, v135, v134
	v_div_fmas_f32 v123, v123, v133, v135
	v_pk_add_f32 v[34:35], v[34:35], 1.0 op_sel_hi:[1,0]
	v_div_fixup_f32 v41, v123, v41, 1.0
	v_div_scale_f32 v123, s[16:17], v35, v35, 1.0
	v_rcp_f32_e32 v133, v123
	v_add_f32_e32 v36, v196, v147
	v_add_f32_e32 v37, v197, v148
	v_mul_f32_e32 v36, 0xbfb8aa3b, v36
	v_fma_f32 v134, -v123, v133, 1.0
	v_fmac_f32_e32 v133, v134, v133
	v_div_scale_f32 v134, vcc, 1.0, v35, 1.0
	v_mul_f32_e32 v135, v134, v133
	v_fma_f32 v136, -v123, v135, v134
	v_fmac_f32_e32 v135, v136, v133
	v_fma_f32 v123, -v123, v135, v134
	v_div_scale_f32 v134, s[16:17], v34, v34, 1.0
	v_rcp_f32_e32 v136, v134
	v_mul_f32_e32 v37, 0xbfb8aa3b, v37
	v_exp_f32_e32 v36, v36
	v_exp_f32_e32 v37, v37
	v_div_fmas_f32 v123, v123, v133, v135
	v_div_fixup_f32 v135, v123, v35, 1.0
	v_fma_f32 v35, -v134, v136, 1.0
	v_fmac_f32_e32 v136, v35, v136
	v_div_scale_f32 v35, vcc, 1.0, v34, 1.0
	v_mul_f32_e32 v123, v35, v136
	v_pk_add_f32 v[36:37], v[36:37], 1.0 op_sel_hi:[1,0]
	v_fma_f32 v133, -v134, v123, v35
	v_fmac_f32_e32 v123, v133, v136
	v_div_scale_f32 v133, s[16:17], v37, v37, 1.0
	v_rcp_f32_e32 v137, v133
	v_fma_f32 v35, -v134, v123, v35
	v_div_fmas_f32 v35, v35, v136, v123
	v_div_fixup_f32 v134, v35, v34, 1.0
	v_fma_f32 v34, -v133, v137, 1.0
	v_fmac_f32_e32 v137, v34, v137
	v_div_scale_f32 v34, vcc, 1.0, v37, 1.0
	v_mul_f32_e32 v35, v34, v137
	v_fma_f32 v123, -v133, v35, v34
	v_fmac_f32_e32 v35, v123, v137
	v_div_scale_f32 v123, s[16:17], v36, v36, 1.0
	v_fma_f32 v34, -v133, v35, v34
	v_rcp_f32_e32 v133, v123
	v_div_fmas_f32 v34, v34, v137, v35
	v_div_fixup_f32 v37, v34, v37, 1.0
	v_mul_f32_e32 v38, 0xbf1b4598, v38
	v_fma_f32 v34, -v123, v133, 1.0
	v_fmac_f32_e32 v133, v34, v133
	v_div_scale_f32 v34, vcc, 1.0, v36, 1.0
	v_mul_f32_e32 v35, v34, v133
	v_fma_f32 v136, -v123, v35, v34
	v_fmac_f32_e32 v35, v136, v133
	v_fma_f32 v34, -v123, v35, v34
	v_div_fmas_f32 v34, v34, v133, v35
	v_div_fixup_f32 v36, v34, v36, 1.0
	v_pk_fma_f32 v[34:35], v[48:49], v[204:205], v[92:93]
	v_pk_fma_f32 v[32:33], v[46:47], v[202:203], v[20:21]
	v_pk_add_f32 v[20:21], v[36:37], -1.0 op_sel_hi:[1,0]
	v_pk_add_f32 v[30:31], v[134:135], -1.0 op_sel_hi:[1,0]
	v_pk_fma_f32 v[20:21], v[208:209], v[20:21], 1.0 op_sel_hi:[1,1,0]
	v_pk_fma_f32 v[30:31], v[206:207], v[30:31], 1.0 op_sel_hi:[1,1,0]
	v_pk_mul_f32 v[44:45], v[44:45], v[20:21]
	v_pk_mul_f32 v[42:43], v[42:43], v[30:31]
	v_pk_mul_f32 v[30:31], v[34:35], v[44:45]
	v_pk_mul_f32 v[20:21], v[32:33], v[42:43]
	v_pk_mul_f32 v[30:31], v[212:213], v[30:31]
	v_pk_mul_f32 v[20:21], v[210:211], v[20:21]
	v_mul_f32_e32 v39, 0xbf1b4598, v39
	v_mul_f32_e32 v40, 0xbf1b4598, v40
	v_mul_f32_e32 v41, 0xbf1b4598, v41
	v_add_f32_e32 v20, v20, v21
	v_add_f32_e32 v21, v30, v31
	v_mul_f32_e32 v38, 0x3fb8aa3b, v38
	v_mul_f32_e32 v39, 0x3fb8aa3b, v39
	v_mul_f32_e32 v40, 0x3fb8aa3b, v40
	v_mul_f32_e32 v41, 0x3fb8aa3b, v41
	v_add_f32_e32 v20, v20, v21
	v_exp_f32_e32 v38, v38
	v_exp_f32_e32 v39, v39
	v_exp_f32_e32 v40, v40
	v_exp_f32_e32 v41, v41
	v_add_f32_dpp v20, v20, v20 quad_perm:[1,0,3,2] row_mask:0xf bank_mask:0xf bound_ctrl:1
	v_add_u32_e32 v30, s6, v99
	v_mov_b32_e32 v21, 0
	v_add_f32_dpp v20, v20, v20 quad_perm:[2,3,0,1] row_mask:0xf bank_mask:0xf bound_ctrl:1
	v_add_u32_e32 v31, v30, v100
	v_pk_mul_f32 v[48:49], v[126:127], v[132:133] op_sel_hi:[1,0]
	v_add_f32_dpp v20, v20, v20 row_half_mirror row_mask:0xf bank_mask:0xf bound_ctrl:1
	v_pk_mul_f32 v[46:47], v[124:125], v[132:133] op_sel_hi:[1,0]
	ds_write_b128 v31, v[46:49]
	ds_write_b128 v31, v[38:41] offset:256
	v_mov_b32_dpp v21, v20 row_mirror row_mask:0xf bank_mask:0xf
	v_pk_mul_f32 v[38:39], v[48:49], v[36:37] neg_lo:[1,0] neg_hi:[1,0]
	v_pk_mul_f32 v[36:37], v[46:47], v[134:135] neg_lo:[1,0] neg_hi:[1,0]
	v_cmp_eq_u32_e32 vcc, v101, v121
	ds_write_b128 v31, v[36:39] offset:512
	ds_write_b128 v31, v[42:45] offset:768
	ds_write_b128 v31, v[32:35] offset:1024
	s_and_saveexec_b64 s[16:17], vcc
	s_cbranch_execz .LBB0_1631
	v_lshl_add_u64 v[32:33], s[58:59], 0, v[18:19]
	v_add_co_u32_e32 v32, vcc, 0x1000, v32
	v_lshlrev_b32_e32 v36, 16, v234
	s_nop 0
	v_addc_co_u32_e32 v33, vcc, 0, v33, vcc
	v_and_b32_e32 v37, 0xffff0000, v234
	v_lshlrev_b32_e32 v38, 16, v235
	v_and_b32_e32 v39, 0xffff0000, v235
	v_sub_f32_e32 v29, v29, v39
	v_sub_f32_e32 v28, v28, v38
	v_sub_f32_e32 v27, v27, v37
	v_sub_f32_e32 v26, v26, v36
	v_add_u32_e32 v18, v30, v102
	v_pk_fma_f32 v[26:27], v[26:27], v[214:215], v[36:37]
	v_pk_fma_f32 v[28:29], v[28:29], v[216:217], v[38:39]
	ds_write_b128 v18, v[26:29] offset:1280
.LBB0_1631:
	s_or_b64 exec, exec, s[16:17]
	v_or_b32_e32 v18, v121, v97
	v_cmp_eq_u32_e32 vcc, 0, v18
	s_and_b64 exec, exec, vcc
	s_cbranch_execz .LBB0_1633
	v_add_f32_e32 v26, v20, v21
	v_add_u32_e32 v20, v122, v96
	v_ashrrev_i32_e32 v21, 31, v20
	v_lshlrev_b64 v[20:21], 5, v[20:21]
	v_lshl_add_u64 v[20:21], s[38:39], 0, v[20:21]
	v_lshlrev_b32_e32 v18, 2, v91
	v_lshl_add_u64 v[20:21], v[20:21], 0, v[18:19]
	global_store_dword v[20:21], v26, off
	s_add_u32 s99, s99, 1
; __device__ __forceinline__ float sigmoidf_(float x) { return 1.0f / (1.0f + __expf(-x)); }
; __device__ __forceinline__ f32x4 cv_bf4(const u32x2 w) { return (f32x4){bflo(w.x), bfhi(w.x), bflo(w.y), bfhi(w.y)}; }
; __device__ __forceinline__ void scan_finish(const ScanPtrs& Q, int J, int ci, unsigned char* buf, int ltid, const LStage& L, int toff) {
;     ...
;     if (tt < jb.nsteps) {
;         const int tok = jb.tok0 + tt; const int tseq = jb.is_s ? tt : ci * SC_CH + tt;
;         const int gc = jb.h * 64 + c;
;         f32x4 r = cv_bf4(L.r), k0 = cv_bf4(L.k), v = cv_bf4(L.v), rp, kp, vp;
;         if (tseq > 0) { rp = cv_bf4(L.rp); kp = cv_bf4(L.kp); vp = cv_bf4(L.vp); }
;         else if (jb.is_s) { rp = L.fr; kp = L.fk; vp = L.fv; }
;         else { rp = (f32x4){0.f, 0.f, 0.f, 0.f}; kp = rp; vp = rp; }
;         const float* mu = Q.mu + gc;
;         r = r + (rp - r) * *(const f32x4*)mu; k0 = k0 + (kp - k0) * *(const f32x4*)(mu + 512); v = v + (vp - v) * *(const f32x4*)(mu + 1024);
;         const f32x4 kk = k0 * *(const f32x4*)(Q.k_k + gc);
;         const float ss = allsum16((kk[0] * kk[0] + kk[1] * kk[1]) + (kk[2] * kk[2] + kk[3] * kk[3]));
;         const float inv = 1.0f / fmaxf(sqrtf(ss), 1e-12f);
;         const f32x4 kkn = kk * inv;
;         const f32x4 dw = cv_bf4(L.sw) + *(const f32x4*)(Q.decay0 + gc);
;         const f32x4 da = cv_bf4(L.sa) + *(const f32x4*)(Q.a0 + gc);
;         f32x4 dec, ain;
; #pragma unroll
;         for (int j = 0; j < 4; ++j) { dec[j] = __expf(-0.60653066f * sigmoidf_(dw[j])); ain[j] = sigmoidf_(da[j]); }
;         const f32x4 ka = *(const f32x4*)(Q.k_a + gc);
;         const f32x4 kf = k0 * (1.0f + (ain - 1.0f) * ka);
;         const f32x4 rkw = *(const f32x4*)(Q.r_k + gc);
;         const f32x4 pr = r * kf * rkw;
;         const float rk = allsum16((pr[0] + pr[1]) + (pr[2] + pr[3]));
.LBB0_1633:
	s_or_b64 exec, exec, s[72:73]
	s_nor_b64 s[16:17], s[14:15], s[8:9]
	v_cndmask_b32_e64 v18, 64, 1, s[14:15]
	s_and_saveexec_b64 s[20:21], s[16:17]
	s_cbranch_execz .LBB0_1641
	v_cmp_gt_i32_e32 vcc, v120, v104
	v_mov_b32_e32 v48, 0
	v_mov_b32_e32 v49, 0
	v_mov_b32_e32 v50, 0
	v_mov_b32_e32 v51, 0
	v_mov_b32_e32 v52, 0
	v_mov_b32_e32 v92, 0
	v_mov_b32_e32 v53, 0
	v_mov_b32_e32 v93, 0
	v_mov_b32_e32 v44, 0
	v_mov_b32_e32 v45, 0
	v_mov_b32_e32 v46, 0
	v_mov_b32_e32 v47, 0
	s_and_saveexec_b64 s[14:15], vcc
	s_cbranch_execz .LBB0_1636
	v_lshlrev_b32_e32 v44, 16, v170
	v_and_b32_e32 v45, 0xffff0000, v170
	v_lshlrev_b32_e32 v46, 16, v171
	v_and_b32_e32 v47, 0xffff0000, v171
	v_lshlrev_b32_e32 v52, 16, v174
	v_and_b32_e32 v92, 0xffff0000, v174
	v_lshlrev_b32_e32 v53, 16, v175
	v_and_b32_e32 v93, 0xffff0000, v175
	v_lshlrev_b32_e32 v48, 16, v182
	v_and_b32_e32 v49, 0xffff0000, v182
	v_lshlrev_b32_e32 v50, 16, v183
	v_and_b32_e32 v51, 0xffff0000, v183
.LBB0_1636:
	s_or_b64 exec, exec, s[14:15]
	v_lshl_or_b32 v18, v91, 8, v100
	v_lshlrev_b32_e32 v134, 16, v176
	v_and_b32_e32 v135, 0xffff0000, v176
	v_lshlrev_b32_e32 v136, 16, v177
	v_and_b32_e32 v137, 0xffff0000, v177
	v_sub_f32_e32 v139, v92, v135
	v_sub_f32_e32 v138, v52, v134
	v_sub_f32_e32 v93, v93, v137
	v_sub_f32_e32 v92, v53, v136
	v_lshlrev_b32_e32 v140, 16, v240
	v_and_b32_e32 v141, 0xffff0000, v240
	v_lshlrev_b32_e32 v142, 16, v241
	v_lshlrev_b32_e32 v146, 16, v242
	v_and_b32_e32 v143, 0xffff0000, v241
	v_and_b32_e32 v147, 0xffff0000, v242
	v_lshlrev_b32_e32 v148, 16, v243
	v_and_b32_e32 v149, 0xffff0000, v243
	v_lshlrev_b32_e32 v20, 16, v172
	v_and_b32_e32 v21, 0xffff0000, v172
	v_lshlrev_b32_e32 v42, 16, v173
	v_and_b32_e32 v43, 0xffff0000, v173
	v_sub_f32_e32 v45, v45, v21
	v_sub_f32_e32 v44, v44, v20
	v_sub_f32_e32 v47, v47, v43
	v_sub_f32_e32 v46, v46, v42
	v_pk_fma_f32 v[40:41], v[92:93], v[188:189], v[136:137]
	v_pk_fma_f32 v[38:39], v[138:139], v[186:187], v[134:135]
	v_add_f32_e32 v34, v190, v140
	v_add_f32_e32 v35, v191, v141
	v_pk_mul_f32 v[52:53], v[40:41], v[200:201]
	v_pk_mul_f32 v[92:93], v[38:39], v[198:199]
	v_mul_f32_e32 v124, 0xbfb8aa3b, v34
	v_mul_f32_e32 v125, 0xbfb8aa3b, v35
	v_pk_mul_f32 v[34:35], v[52:53], v[52:53]
	v_pk_mul_f32 v[122:123], v[92:93], v[92:93]
	v_exp_f32_e32 v134, v124
	v_exp_f32_e32 v135, v125
	v_pk_mov_b32 v[124:125], v[122:123], v[34:35] op_sel:[1,0]
	v_mov_b32_e32 v123, v35
	v_pk_add_f32 v[34:35], v[124:125], v[122:123]
	v_add_f32_e32 v123, 1.0, v135
	v_add_f32_e32 v34, v34, v35
	v_add_f32_e32 v35, 1.0, v134
	v_div_scale_f32 v122, s[14:15], v35, v35, 1.0
	v_add_f32_dpp v34, v34, v34 quad_perm:[1,0,3,2] row_mask:0xf bank_mask:0xf bound_ctrl:1
	v_div_scale_f32 v125, s[16:17], v123, v123, 1.0
	s_nop 0
	v_add_f32_dpp v34, v34, v34 quad_perm:[2,3,0,1] row_mask:0xf bank_mask:0xf bound_ctrl:1
	v_rcp_f32_e32 v135, v122
	v_rcp_f32_e32 v136, v125
	v_add_f32_dpp v34, v34, v34 row_half_mirror row_mask:0xf bank_mask:0xf bound_ctrl:1
	v_div_scale_f32 v124, s[14:15], 1.0, v35, 1.0
	s_nop 0
	v_add_f32_dpp v34, v34, v34 row_mirror row_mask:0xf bank_mask:0xf bound_ctrl:1
	v_mul_f32_e32 v137, 0x4f800000, v34
	v_cmp_gt_f32_e32 vcc, s77, v34
	v_fma_f32 v138, -v122, v135, 1.0
	v_fma_f32 v139, -v125, v136, 1.0
	v_cndmask_b32_e32 v34, v34, v137, vcc
	v_sqrt_f32_e32 v137, v34
	v_fmac_f32_e32 v135, v138, v135
	v_div_scale_f32 v134, s[16:17], 1.0, v123, 1.0
	v_fmac_f32_e32 v136, v139, v136
	v_mul_f32_e32 v138, v124, v135
	v_add_f32_e32 v36, v192, v142
	v_mul_f32_e32 v139, v134, v136
	v_fma_f32 v140, -v122, v138, v124
	v_add_u32_e32 v142, -1, v137
	v_add_f32_e32 v30, v194, v146
	v_fma_f32 v141, -v125, v139, v134
	v_add_u32_e32 v146, 1, v137
	v_fmac_f32_e32 v138, v140, v135
	v_fma_f32 v140, -v142, v137, v34
	v_fmac_f32_e32 v139, v141, v136
	v_fma_f32 v141, -v146, v137, v34
	v_cmp_ge_f32_e64 s[18:19], 0, v140
	v_fma_f32 v124, -v122, v138, v124
	v_fma_f32 v125, -v125, v139, v134
	v_cndmask_b32_e64 v122, v137, v142, s[18:19]
	v_cmp_lt_f32_e64 s[18:19], 0, v141
	v_mul_f32_e32 v36, 0xbfb8aa3b, v36
	v_exp_f32_e32 v36, v36
	v_cndmask_b32_e64 v122, v122, v146, s[18:19]
	v_mul_f32_e32 v137, 0x37800000, v122
	v_cndmask_b32_e32 v122, v122, v137, vcc
	v_cmp_class_f32_e32 vcc, v34, v118
	v_add_f32_e32 v36, 1.0, v36
	v_add_f32_e32 v37, v193, v143
	v_cndmask_b32_e32 v34, v122, v34, vcc
	v_max_f32_e32 v34, 0x2b8cbccc, v34
	v_div_scale_f32 v122, s[18:19], v34, v34, -1.0
	v_rcp_f32_e32 v137, v122
	v_div_scale_f32 v134, vcc, -1.0, v34, -1.0
	v_mul_f32_e32 v37, 0xbfb8aa3b, v37
	v_fma_f32 v140, -v122, v137, 1.0
	v_fmac_f32_e32 v137, v140, v137
	v_mul_f32_e32 v140, v134, v137
	v_fma_f32 v141, -v122, v140, v134
	v_fmac_f32_e32 v140, v141, v137
	v_fma_f32 v122, -v122, v140, v134
	v_div_fmas_f32 v122, v122, v137, v140
	s_mov_b64 vcc, s[14:15]
	v_div_fixup_f32 v122, v122, v34, -1.0
	v_div_fmas_f32 v34, v124, v135, v138
	s_mov_b64 vcc, s[16:17]
	v_div_fixup_f32 v34, v34, v35, 1.0
	v_div_fmas_f32 v35, v125, v136, v139
	v_div_fixup_f32 v35, v35, v123, 1.0
	v_div_scale_f32 v123, s[14:15], v36, v36, 1.0
	v_rcp_f32_e32 v124, v123
	v_exp_f32_e32 v37, v37
	v_add_f32_e32 v31, v195, v147
	v_mul_f32_e32 v30, 0xbfb8aa3b, v30
	v_fma_f32 v125, -v123, v124, 1.0
	v_fmac_f32_e32 v124, v125, v124
	v_div_scale_f32 v125, vcc, 1.0, v36, 1.0
	v_mul_f32_e32 v134, v125, v124
	v_fma_f32 v135, -v123, v134, v125
	v_fmac_f32_e32 v134, v135, v124
	v_fma_f32 v123, -v123, v134, v125
	v_div_fmas_f32 v123, v123, v124, v134
	v_add_f32_e32 v37, 1.0, v37
	v_div_fixup_f32 v36, v123, v36, 1.0
; __device__ __forceinline__ float sigmoidf_(float x) { return 1.0f / (1.0f + __expf(-x)); }
; __device__ __forceinline__ f32x4 cv_bf4(const u32x2 w) { return (f32x4){bflo(w.x), bfhi(w.x), bflo(w.y), bfhi(w.y)}; }
; __device__ __forceinline__ void scan_finish(const ScanPtrs& Q, int J, int ci, unsigned char* buf, int ltid, const LStage& L, int toff) {
;     ...
;         const f32x4 dw = cv_bf4(L.sw) + *(const f32x4*)(Q.decay0 + gc);
;         const f32x4 da = cv_bf4(L.sa) + *(const f32x4*)(Q.a0 + gc);
;         f32x4 dec, ain;
; #pragma unroll
;         for (int j = 0; j < 4; ++j) { dec[j] = __expf(-0.60653066f * sigmoidf_(dw[j])); ain[j] = sigmoidf_(da[j]); }
;         const f32x4 ka = *(const f32x4*)(Q.k_a + gc);
;         const f32x4 kf = k0 * (1.0f + (ain - 1.0f) * ka);
;         const f32x4 rkw = *(const f32x4*)(Q.r_k + gc);
;         const f32x4 pr = r * kf * rkw;
;         const float rk = allsum16((pr[0] + pr[1]) + (pr[2] + pr[3]));
;         unsigned char* tb = buf + tt * SC_TOKB + c * 4;
;         *(f32x4*)(tb) = -kkn; *(f32x4*)(tb + 256) = dec; *(f32x4*)(tb + 512) = kkn * ain; *(f32x4*)(tb + 768) = kf; *(f32x4*)(tb + 1024) = r;
;         if ((c >> 4) == jb.rs) *(f32x4*)(buf + tt * SC_TOKB + 1280 + (c & 15) * 4) = v;
;         if (jb.rs == 0 && c == 0) Q.rk[(size_t)tok * 8 + jb.h] = rk;
	v_div_scale_f32 v123, s[14:15], v37, v37, 1.0
	v_rcp_f32_e32 v124, v123
	v_mul_f32_e32 v31, 0xbfb8aa3b, v31
	v_exp_f32_e32 v30, v30
	v_exp_f32_e32 v31, v31
	v_fma_f32 v125, -v123, v124, 1.0
	v_fmac_f32_e32 v124, v125, v124
	v_div_scale_f32 v125, vcc, 1.0, v37, 1.0
	v_mul_f32_e32 v134, v125, v124
	v_fma_f32 v135, -v123, v134, v125
	v_fmac_f32_e32 v134, v135, v124
	v_fma_f32 v123, -v123, v134, v125
	v_div_fmas_f32 v123, v123, v124, v134
	v_pk_add_f32 v[30:31], v[30:31], 1.0 op_sel_hi:[1,0]
	v_div_fixup_f32 v37, v123, v37, 1.0
	v_div_scale_f32 v123, s[14:15], v31, v31, 1.0
	v_rcp_f32_e32 v124, v123
	v_add_f32_e32 v32, v196, v148
	v_add_f32_e32 v33, v197, v149
	v_mul_f32_e32 v32, 0xbfb8aa3b, v32
	v_fma_f32 v125, -v123, v124, 1.0
	v_fmac_f32_e32 v124, v125, v124
	v_div_scale_f32 v125, vcc, 1.0, v31, 1.0
	v_mul_f32_e32 v134, v125, v124
	v_fma_f32 v135, -v123, v134, v125
	v_fmac_f32_e32 v134, v135, v124
	v_div_scale_f32 v135, s[14:15], v30, v30, 1.0
	v_rcp_f32_e32 v136, v135
	v_mul_f32_e32 v33, 0xbfb8aa3b, v33
	v_fma_f32 v123, -v123, v134, v125
	v_exp_f32_e32 v32, v32
	v_exp_f32_e32 v33, v33
	v_div_fmas_f32 v123, v123, v124, v134
	v_div_fixup_f32 v125, v123, v31, 1.0
	v_fma_f32 v31, -v135, v136, 1.0
	v_fmac_f32_e32 v136, v31, v136
	v_div_scale_f32 v31, vcc, 1.0, v30, 1.0
	v_mul_f32_e32 v123, v31, v136
	v_pk_add_f32 v[32:33], v[32:33], 1.0 op_sel_hi:[1,0]
	v_fma_f32 v124, -v135, v123, v31
	v_fmac_f32_e32 v123, v124, v136
	v_div_scale_f32 v134, s[14:15], v33, v33, 1.0
	v_fma_f32 v31, -v135, v123, v31
	v_rcp_f32_e32 v135, v134
	v_div_fmas_f32 v31, v31, v136, v123
	v_div_fixup_f32 v124, v31, v30, 1.0
	v_mul_f32_e32 v34, 0xbf1b4598, v34
	v_fma_f32 v30, -v134, v135, 1.0
	v_fmac_f32_e32 v135, v30, v135
	v_div_scale_f32 v30, vcc, 1.0, v33, 1.0
	v_mul_f32_e32 v31, v30, v135
	v_fma_f32 v123, -v134, v31, v30
	v_fmac_f32_e32 v31, v123, v135
	v_div_scale_f32 v123, s[14:15], v32, v32, 1.0
	v_fma_f32 v30, -v134, v31, v30
	v_rcp_f32_e32 v134, v123
	v_div_fmas_f32 v30, v30, v135, v31
	v_div_fixup_f32 v33, v30, v33, 1.0
	v_mul_f32_e32 v35, 0xbf1b4598, v35
	v_fma_f32 v30, -v123, v134, 1.0
	v_fmac_f32_e32 v134, v30, v134
	v_div_scale_f32 v30, vcc, 1.0, v32, 1.0
	v_mul_f32_e32 v31, v30, v134
	v_fma_f32 v135, -v123, v31, v30
	v_fmac_f32_e32 v31, v135, v134
	v_fma_f32 v30, -v123, v31, v30
	v_div_fmas_f32 v30, v30, v134, v31
	v_div_fixup_f32 v32, v30, v32, 1.0
	v_pk_fma_f32 v[30:31], v[46:47], v[204:205], v[42:43]
	v_pk_fma_f32 v[28:29], v[44:45], v[202:203], v[20:21]
	v_pk_add_f32 v[20:21], v[32:33], -1.0 op_sel_hi:[1,0]
	v_pk_add_f32 v[26:27], v[124:125], -1.0 op_sel_hi:[1,0]
	v_pk_fma_f32 v[20:21], v[208:209], v[20:21], 1.0 op_sel_hi:[1,1,0]
	v_pk_fma_f32 v[26:27], v[206:207], v[26:27], 1.0 op_sel_hi:[1,1,0]
	v_pk_mul_f32 v[40:41], v[40:41], v[20:21]
	v_pk_mul_f32 v[38:39], v[38:39], v[26:27]
	v_pk_mul_f32 v[26:27], v[30:31], v[40:41]
	v_pk_mul_f32 v[20:21], v[28:29], v[38:39]
	v_pk_mul_f32 v[26:27], v[212:213], v[26:27]
	v_pk_mul_f32 v[20:21], v[210:211], v[20:21]
	v_mul_f32_e32 v36, 0xbf1b4598, v36
	v_mul_f32_e32 v37, 0xbf1b4598, v37
	v_add_f32_e32 v20, v20, v21
	v_add_f32_e32 v21, v26, v27
	v_mul_f32_e32 v34, 0x3fb8aa3b, v34
	v_mul_f32_e32 v35, 0x3fb8aa3b, v35
	v_mul_f32_e32 v36, 0x3fb8aa3b, v36
	v_mul_f32_e32 v37, 0x3fb8aa3b, v37
	v_add_f32_e32 v20, v20, v21
	v_exp_f32_e32 v34, v34
	v_exp_f32_e32 v35, v35
	v_exp_f32_e32 v36, v36
	v_exp_f32_e32 v37, v37
	v_add_f32_dpp v20, v20, v20 quad_perm:[1,0,3,2] row_mask:0xf bank_mask:0xf bound_ctrl:1
	v_add_u32_e32 v26, s6, v105
	v_mov_b32_e32 v21, 0
	v_add_f32_dpp v20, v20, v20 quad_perm:[2,3,0,1] row_mask:0xf bank_mask:0xf bound_ctrl:1
	v_add_u32_e32 v27, v26, v100
	v_pk_mul_f32 v[44:45], v[52:53], v[122:123] op_sel_hi:[1,0]
	v_add_f32_dpp v20, v20, v20 row_half_mirror row_mask:0xf bank_mask:0xf bound_ctrl:1
	v_pk_mul_f32 v[42:43], v[92:93], v[122:123] op_sel_hi:[1,0]
	ds_write_b128 v27, v[42:45]
	ds_write_b128 v27, v[34:37] offset:256
	v_mov_b32_dpp v21, v20 row_mirror row_mask:0xf bank_mask:0xf
	v_pk_mul_f32 v[34:35], v[44:45], v[32:33] neg_lo:[1,0] neg_hi:[1,0]
	v_pk_mul_f32 v[32:33], v[42:43], v[124:125] neg_lo:[1,0] neg_hi:[1,0]
	v_cmp_eq_u32_e32 vcc, v101, v121
	ds_write_b128 v27, v[32:35] offset:512
	ds_write_b128 v27, v[38:41] offset:768
	ds_write_b128 v27, v[28:31] offset:1024
	s_and_saveexec_b64 s[14:15], vcc
	s_cbranch_execz .LBB0_1638
	v_lshl_add_u64 v[28:29], s[58:59], 0, v[18:19]
	v_add_co_u32_e32 v28, vcc, 0x1000, v28
	v_lshlrev_b32_e32 v32, 16, v184
	s_nop 0
	v_addc_co_u32_e32 v29, vcc, 0, v29, vcc
	v_and_b32_e32 v33, 0xffff0000, v184
	v_lshlrev_b32_e32 v34, 16, v185
	v_and_b32_e32 v35, 0xffff0000, v185
	v_add_u32_e32 v18, v26, v102
	v_sub_f32_e32 v37, v51, v35
	v_sub_f32_e32 v36, v50, v34
	v_sub_f32_e32 v27, v49, v33
	v_sub_f32_e32 v26, v48, v32
	v_pk_fma_f32 v[26:27], v[26:27], v[214:215], v[32:33]
	v_pk_fma_f32 v[28:29], v[36:37], v[216:217], v[34:35]
	ds_write_b128 v18, v[26:29] offset:1280
.LBB0_1638:
	s_or_b64 exec, exec, s[14:15]
	v_or_b32_e32 v18, v121, v97
	v_cmp_eq_u32_e32 vcc, 0, v18
	s_and_saveexec_b64 s[14:15], vcc
	s_cbranch_execz .LBB0_1640
	v_lshlrev_b32_e32 v18, 6, v94
	v_and_b32_e32 v18, 0xfffff800, v18
	v_add_u32_e32 v18, v18, v120
	v_add_f32_e32 v26, v20, v21
	v_or_b32_e32 v20, v18, v103
	v_ashrrev_i32_e32 v21, 31, v20
	v_lshlrev_b64 v[20:21], 5, v[20:21]
	v_lshl_add_u64 v[20:21], s[38:39], 0, v[20:21]
	v_lshlrev_b32_e32 v18, 2, v91
	v_lshl_add_u64 v[20:21], v[20:21], 0, v[18:19]
	global_store_dword v[20:21], v26, off
	s_add_u32 s99, s99, 1

; #define SC_ADV(J_, c_) do { if ((J_) < NJOBS) { if (++(c_) >= ((J_) < 256 ? SEQ / SC_CH : 1)) { (J_) += G; (c_) = 0; } } } while (0)
; __device__ void phase_scan(int l, unsigned char* lds) {
;     ...
;             if (Jg < NJOBS) { scan_finish(Q, Jg, cg_, lds + ((it + 2) % 3) * SC_BUFB, tid - 256, L, 0); scan_finish(Q, Jg, cg_, lds + ((it + 2) % 3) * SC_BUFB, tid - 256, L2, 16); }
;             SC_ADV(Jg, cg_);
;             if (Ji < NJOBS) { scan_issue(Q, Ji, cis, tid - 256, L, 0); scan_issue(Q, Ji, cis, tid - 256, L2, 16); }
;             SC_ADV(Ji, cis);
.LBB0_1642:
	s_or_b64 exec, exec, s[70:71]
.LBB0_1663:
	s_or_saveexec_b64 s[14:15], s[68:69]
	s_add_i32 s6, s86, s53
	s_xor_b64 exec, exec, s[14:15]
	s_cbranch_execz .LBB0_1615
	s_mov_b64 s[16:17], -1
	s_and_b64 vcc, exec, s[66:67]
	s_cbranch_vccz .LBB0_1666
	s_add_i32 s7, s53, 0xffffff00
	s_lshr_b32 s7, s7, 5
	s_lshl_b32 s16, s7, 3
	s_add_i32 s33, s16, 0x4000
	s_mov_b64 s[16:17], 0
